# RW scan: 16-step chunk fully unrolled, bf16 store via v_cvt_pk + SGPR-base global_store_short (46 instr/step)
# baseline (speedup 1.0000x reference)
.LBB0_850:
	s_or_b64 exec, exec, s[16:17]
	s_waitcnt lgkmcnt(0)
	s_barrier
	s_and_saveexec_b64 s[6:7], vcc
	s_xor_b64 s[16:17], exec, s[6:7]
	s_cbranch_execz .LBB0_1083
	s_setprio 3
	v_readlane_b32 s2, v255, 2
	s_add_u32 s2, s14, s2
	v_readlane_b32 s4, v253, 59
	s_addc_u32 s3, s15, 0
	s_waitcnt vmcnt(4)
	v_lshlrev_b32_e32 v5, 3, v13
	s_waitcnt vmcnt(3)
	v_bfe_u32 v6, v14, 3, 3
	v_readlane_b32 s8, v253, 58
	s_lshl_b32 s4, s4, 1
	s_add_u32 s6, s2, s4
	s_waitcnt vmcnt(2)
	v_or3_b32 v7, v5, s8, v6
	s_addc_u32 s7, s3, 0
	v_lshlrev_b32_e32 v0, 1, v7
	v_and_b32_e32 v4, 7, v14
	v_lshl_add_u64 v[2:3], s[6:7], 0, v[0:1]
	s_mov_b64 s[2:3], 0x11435800
	v_add_u32_e32 v0, s8, v5
	v_mov_b32_e32 v84, 0
	v_lshl_add_u64 v[82:83], v[2:3], 0, s[2:3]
	v_lshlrev_b32_e32 v100, 5, v4
	v_lshlrev_b32_e32 v101, 2, v7
	s_mov_b32 s4, 0
	v_cmp_eq_u32_e64 s[44:45], 0, v4
	v_add_lshl_u32 v102, v0, v6, 2
	v_mov_b32_e32 v85, v84
	v_mov_b32_e32 v86, v84
	v_mov_b32_e32 v87, v84
	v_mov_b32_e32 v88, v84
	v_mov_b32_e32 v89, v84
	v_mov_b32_e32 v90, v84
	v_mov_b32_e32 v91, v84
	s_waitcnt vmcnt(0)
	v_readlane_b32 s101, v254, 61
	v_readfirstlane_b32 s100, v82
	s_lshl_b32 s101, s101, 9
	s_cmp_lt_i32 s101, 0
	s_cselect_b32 m0, 0x1e00, 0
	v_subrev_u32_e32 v160, s100, v82
	v_add_u32_e32 v144, m0, v160
	v_add_u32_e32 v145, s101, v144
	v_add_u32_e32 v146, s101, v145
	v_add_u32_e32 v147, s101, v146
	v_add_u32_e32 v148, s101, v147
	v_add_u32_e32 v149, s101, v148
	v_add_u32_e32 v150, s101, v149
	v_add_u32_e32 v151, s101, v150
	v_add_u32_e32 v152, s101, v151
	v_add_u32_e32 v153, s101, v152
	v_add_u32_e32 v154, s101, v153
	v_add_u32_e32 v155, s101, v154
	v_add_u32_e32 v156, s101, v155
	v_add_u32_e32 v157, s101, v156
	v_add_u32_e32 v158, s101, v157
	v_add_u32_e32 v159, s101, v158
	s_branch .LBB0_853

.LBB0_859:
	v_readfirstlane_b32 s100, v92
	v_readfirstlane_b32 s101, v93
	s_sub_u32 s100, s100, m0
	s_subb_u32 s101, s101, 0
	s_waitcnt lgkmcnt(0)
	v_pk_fma_f32 v[106:107], v[84:85], v[34:35], 0 op_sel_hi:[1,1,0]
	v_pk_fma_f32 v[108:109], v[84:85], v[22:23], 0 op_sel_hi:[1,1,0]
	ds_read_b128 v[70:73], v100 offset:1568
	ds_read_b128 v[66:69], v100 offset:1584
	v_pk_fma_f32 v[106:107], v[86:87], v[36:37], v[106:107]
	v_pk_fma_f32 v[108:109], v[86:87], v[24:25], v[108:109]
	ds_read_b128 v[50:53], v100 offset:1824
	ds_read_b128 v[46:49], v100 offset:1840
	v_pk_fma_f32 v[106:107], v[88:89], v[38:39], v[106:107]
	v_pk_fma_f32 v[108:109], v[88:89], v[18:19], v[108:109]
	ds_read_b128 v[54:57], v100 offset:2080
	ds_read_b128 v[42:45], v100 offset:2096
	v_pk_fma_f32 v[106:107], v[90:91], v[40:41], v[106:107]
	v_pk_fma_f32 v[108:109], v[90:91], v[20:21], v[108:109]
	ds_read_b128 v[78:81], v100 offset:2336
	ds_read_b128 v[74:77], v100 offset:2352
	v_add_f32_e32 v130, v106, v107
	v_add_f32_e32 v131, v108, v109
	v_pk_mul_f32 v[114:115], v[84:85], v[2:3]
	v_add_f32_dpp v130, v130, v130 quad_perm:[1,0,3,2] row_mask:0xf bank_mask:0xf bound_ctrl:1
	v_add_f32_dpp v131, v131, v131 quad_perm:[1,0,3,2] row_mask:0xf bank_mask:0xf bound_ctrl:1
	v_pk_mul_f32 v[116:117], v[86:87], v[4:5]
	v_add_f32_dpp v130, v130, v130 quad_perm:[2,3,0,1] row_mask:0xf bank_mask:0xf bound_ctrl:1
	v_add_f32_dpp v131, v131, v131 quad_perm:[2,3,0,1] row_mask:0xf bank_mask:0xf bound_ctrl:1
	v_pk_mul_f32 v[118:119], v[88:89], v[6:7]
	v_add_f32_dpp v130, v130, v130 row_half_mirror row_mask:0xf bank_mask:0xf bound_ctrl:1
	v_add_f32_dpp v131, v131, v131 row_half_mirror row_mask:0xf bank_mask:0xf bound_ctrl:1
	v_pk_mul_f32 v[120:121], v[90:91], v[8:9]
	ds_read_b128 v[62:65], v100 offset:2592
	ds_read_b128 v[58:61], v100 offset:2608
	v_mul_f32_e32 v132, v130, v96
	v_mul_f32_e32 v133, v97, v94
	ds_read_b32 v0, v101 offset:2848
	v_add_f32_e32 v131, v132, v131
	ds_read_b64 v[98:99], v1 offset:3104
	v_add_f32_e32 v131, v133, v131
	v_pk_fma_f32 v[114:115], v[130:131], v[26:27], v[114:115] op_sel_hi:[0,1,1]
	v_pk_fma_f32 v[116:117], v[130:131], v[28:29], v[116:117] op_sel_hi:[0,1,1]
	v_cvt_pk_bf16_f32 v132, v131, v131
	v_pk_fma_f32 v[84:85], v[94:95], v[10:11], v[114:115] op_sel_hi:[0,1,1]
	global_store_short v144, v132, s[100:101]
	v_pk_fma_f32 v[118:119], v[130:131], v[30:31], v[118:119] op_sel_hi:[0,1,1]
	v_pk_fma_f32 v[86:87], v[94:95], v[12:13], v[116:117] op_sel_hi:[0,1,1]
	v_pk_fma_f32 v[120:121], v[130:131], v[32:33], v[120:121] op_sel_hi:[0,1,1]
	v_pk_fma_f32 v[88:89], v[94:95], v[14:15], v[118:119] op_sel_hi:[0,1,1]
	v_pk_fma_f32 v[90:91], v[94:95], v[16:17], v[120:121] op_sel_hi:[0,1,1]
	s_waitcnt lgkmcnt(0)
	v_pk_fma_f32 v[110:111], v[84:85], v[78:79], 0 op_sel_hi:[1,1,0]
	v_pk_fma_f32 v[112:113], v[84:85], v[70:71], 0 op_sel_hi:[1,1,0]
	ds_read_b128 v[22:25], v100 offset:3136
	ds_read_b128 v[18:21], v100 offset:3152
	v_pk_fma_f32 v[110:111], v[86:87], v[80:81], v[110:111]
	v_pk_fma_f32 v[112:113], v[86:87], v[72:73], v[112:113]
	ds_read_b128 v[2:5], v100 offset:3392
	ds_read_b128 v[6:9], v100 offset:3408
	v_pk_fma_f32 v[110:111], v[88:89], v[74:75], v[110:111]
	v_pk_fma_f32 v[112:113], v[88:89], v[66:67], v[112:113]
	ds_read_b128 v[10:13], v100 offset:3648
	ds_read_b128 v[14:17], v100 offset:3664
	v_pk_fma_f32 v[110:111], v[90:91], v[76:77], v[110:111]
	v_pk_fma_f32 v[112:113], v[90:91], v[68:69], v[112:113]
	ds_read_b128 v[34:37], v100 offset:3904
	ds_read_b128 v[38:41], v100 offset:3920
	v_add_f32_e32 v140, v110, v111
	v_add_f32_e32 v141, v112, v113
	v_pk_mul_f32 v[114:115], v[84:85], v[50:51]
	v_add_f32_dpp v140, v140, v140 quad_perm:[1,0,3,2] row_mask:0xf bank_mask:0xf bound_ctrl:1
	v_add_f32_dpp v141, v141, v141 quad_perm:[1,0,3,2] row_mask:0xf bank_mask:0xf bound_ctrl:1
	v_pk_mul_f32 v[116:117], v[86:87], v[52:53]
	v_add_f32_dpp v140, v140, v140 quad_perm:[2,3,0,1] row_mask:0xf bank_mask:0xf bound_ctrl:1
	v_add_f32_dpp v141, v141, v141 quad_perm:[2,3,0,1] row_mask:0xf bank_mask:0xf bound_ctrl:1
	v_pk_mul_f32 v[118:119], v[88:89], v[46:47]
	v_add_f32_dpp v140, v140, v140 row_half_mirror row_mask:0xf bank_mask:0xf bound_ctrl:1
	v_add_f32_dpp v141, v141, v141 row_half_mirror row_mask:0xf bank_mask:0xf bound_ctrl:1
	v_pk_mul_f32 v[120:121], v[90:91], v[48:49]
	ds_read_b128 v[26:29], v100 offset:4160
	ds_read_b128 v[30:33], v100 offset:4176
	v_mul_f32_e32 v142, v140, v98
	v_mul_f32_e32 v143, v99, v0
	ds_read_b32 v94, v101 offset:4416
	v_add_f32_e32 v141, v142, v141
	ds_read_b64 v[96:97], v1 offset:4672
	v_add_f32_e32 v141, v143, v141
	v_pk_fma_f32 v[114:115], v[140:141], v[62:63], v[114:115] op_sel_hi:[0,1,1]
	v_pk_fma_f32 v[116:117], v[140:141], v[64:65], v[116:117] op_sel_hi:[0,1,1]
	v_cvt_pk_bf16_f32 v142, v141, v141
	v_pk_fma_f32 v[84:85], v[0:1], v[54:55], v[114:115] op_sel_hi:[0,1,1]
	global_store_short v145, v142, s[100:101]
	v_pk_fma_f32 v[118:119], v[140:141], v[58:59], v[118:119] op_sel_hi:[0,1,1]
	v_pk_fma_f32 v[86:87], v[0:1], v[56:57], v[116:117] op_sel_hi:[0,1,1]
	v_pk_fma_f32 v[120:121], v[140:141], v[60:61], v[120:121] op_sel_hi:[0,1,1]
	v_pk_fma_f32 v[88:89], v[0:1], v[42:43], v[118:119] op_sel_hi:[0,1,1]
	v_pk_fma_f32 v[90:91], v[0:1], v[44:45], v[120:121] op_sel_hi:[0,1,1]
	s_waitcnt lgkmcnt(0)
	v_pk_fma_f32 v[106:107], v[84:85], v[34:35], 0 op_sel_hi:[1,1,0]
	v_pk_fma_f32 v[108:109], v[84:85], v[22:23], 0 op_sel_hi:[1,1,0]
	ds_read_b128 v[70:73], v100 offset:4704
	ds_read_b128 v[66:69], v100 offset:4720
	v_pk_fma_f32 v[106:107], v[86:87], v[36:37], v[106:107]
	v_pk_fma_f32 v[108:109], v[86:87], v[24:25], v[108:109]
	ds_read_b128 v[50:53], v100 offset:4960
	ds_read_b128 v[46:49], v100 offset:4976
	v_pk_fma_f32 v[106:107], v[88:89], v[38:39], v[106:107]
	v_pk_fma_f32 v[108:109], v[88:89], v[18:19], v[108:109]
	ds_read_b128 v[54:57], v100 offset:5216
	ds_read_b128 v[42:45], v100 offset:5232
	v_pk_fma_f32 v[106:107], v[90:91], v[40:41], v[106:107]
	v_pk_fma_f32 v[108:109], v[90:91], v[20:21], v[108:109]
	ds_read_b128 v[78:81], v100 offset:5472
	ds_read_b128 v[74:77], v100 offset:5488
	v_add_f32_e32 v130, v106, v107
	v_add_f32_e32 v131, v108, v109
	v_pk_mul_f32 v[114:115], v[84:85], v[2:3]
	v_add_f32_dpp v130, v130, v130 quad_perm:[1,0,3,2] row_mask:0xf bank_mask:0xf bound_ctrl:1
	v_add_f32_dpp v131, v131, v131 quad_perm:[1,0,3,2] row_mask:0xf bank_mask:0xf bound_ctrl:1
	v_pk_mul_f32 v[116:117], v[86:87], v[4:5]
	v_add_f32_dpp v130, v130, v130 quad_perm:[2,3,0,1] row_mask:0xf bank_mask:0xf bound_ctrl:1
	v_add_f32_dpp v131, v131, v131 quad_perm:[2,3,0,1] row_mask:0xf bank_mask:0xf bound_ctrl:1
	v_pk_mul_f32 v[118:119], v[88:89], v[6:7]
	v_add_f32_dpp v130, v130, v130 row_half_mirror row_mask:0xf bank_mask:0xf bound_ctrl:1
	v_add_f32_dpp v131, v131, v131 row_half_mirror row_mask:0xf bank_mask:0xf bound_ctrl:1
	v_pk_mul_f32 v[120:121], v[90:91], v[8:9]
	ds_read_b128 v[62:65], v100 offset:5728
	ds_read_b128 v[58:61], v100 offset:5744
	v_mul_f32_e32 v132, v130, v96
	v_mul_f32_e32 v133, v97, v94
	ds_read_b32 v0, v101 offset:5984
	v_add_f32_e32 v131, v132, v131
	ds_read_b64 v[98:99], v1 offset:6240
	v_add_f32_e32 v131, v133, v131
	v_pk_fma_f32 v[114:115], v[130:131], v[26:27], v[114:115] op_sel_hi:[0,1,1]
	v_pk_fma_f32 v[116:117], v[130:131], v[28:29], v[116:117] op_sel_hi:[0,1,1]
	v_cvt_pk_bf16_f32 v132, v131, v131
	v_pk_fma_f32 v[84:85], v[94:95], v[10:11], v[114:115] op_sel_hi:[0,1,1]
	global_store_short v146, v132, s[100:101]
	v_pk_fma_f32 v[118:119], v[130:131], v[30:31], v[118:119] op_sel_hi:[0,1,1]
	v_pk_fma_f32 v[86:87], v[94:95], v[12:13], v[116:117] op_sel_hi:[0,1,1]
	v_pk_fma_f32 v[120:121], v[130:131], v[32:33], v[120:121] op_sel_hi:[0,1,1]
	v_pk_fma_f32 v[88:89], v[94:95], v[14:15], v[118:119] op_sel_hi:[0,1,1]
	v_pk_fma_f32 v[90:91], v[94:95], v[16:17], v[120:121] op_sel_hi:[0,1,1]
	s_waitcnt lgkmcnt(0)
	v_pk_fma_f32 v[110:111], v[84:85], v[78:79], 0 op_sel_hi:[1,1,0]
	v_pk_fma_f32 v[112:113], v[84:85], v[70:71], 0 op_sel_hi:[1,1,0]
	ds_read_b128 v[22:25], v100 offset:6272
	ds_read_b128 v[18:21], v100 offset:6288
	v_pk_fma_f32 v[110:111], v[86:87], v[80:81], v[110:111]
	v_pk_fma_f32 v[112:113], v[86:87], v[72:73], v[112:113]
	ds_read_b128 v[2:5], v100 offset:6528
	ds_read_b128 v[6:9], v100 offset:6544
	v_pk_fma_f32 v[110:111], v[88:89], v[74:75], v[110:111]
	v_pk_fma_f32 v[112:113], v[88:89], v[66:67], v[112:113]
	ds_read_b128 v[10:13], v100 offset:6784
	ds_read_b128 v[14:17], v100 offset:6800
	v_pk_fma_f32 v[110:111], v[90:91], v[76:77], v[110:111]
	v_pk_fma_f32 v[112:113], v[90:91], v[68:69], v[112:113]
	ds_read_b128 v[34:37], v100 offset:7040
	ds_read_b128 v[38:41], v100 offset:7056
	v_add_f32_e32 v140, v110, v111
	v_add_f32_e32 v141, v112, v113
	v_pk_mul_f32 v[114:115], v[84:85], v[50:51]
	v_add_f32_dpp v140, v140, v140 quad_perm:[1,0,3,2] row_mask:0xf bank_mask:0xf bound_ctrl:1
	v_add_f32_dpp v141, v141, v141 quad_perm:[1,0,3,2] row_mask:0xf bank_mask:0xf bound_ctrl:1
	v_pk_mul_f32 v[116:117], v[86:87], v[52:53]
	v_add_f32_dpp v140, v140, v140 quad_perm:[2,3,0,1] row_mask:0xf bank_mask:0xf bound_ctrl:1
	v_add_f32_dpp v141, v141, v141 quad_perm:[2,3,0,1] row_mask:0xf bank_mask:0xf bound_ctrl:1
	v_pk_mul_f32 v[118:119], v[88:89], v[46:47]
	v_add_f32_dpp v140, v140, v140 row_half_mirror row_mask:0xf bank_mask:0xf bound_ctrl:1
	v_add_f32_dpp v141, v141, v141 row_half_mirror row_mask:0xf bank_mask:0xf bound_ctrl:1
	v_pk_mul_f32 v[120:121], v[90:91], v[48:49]
	ds_read_b128 v[26:29], v100 offset:7296
	ds_read_b128 v[30:33], v100 offset:7312
	v_mul_f32_e32 v142, v140, v98
	v_mul_f32_e32 v143, v99, v0
	ds_read_b32 v94, v101 offset:7552
	v_add_f32_e32 v141, v142, v141
	ds_read_b64 v[96:97], v1 offset:7808
	v_add_f32_e32 v141, v143, v141
	v_pk_fma_f32 v[114:115], v[140:141], v[62:63], v[114:115] op_sel_hi:[0,1,1]
	v_pk_fma_f32 v[116:117], v[140:141], v[64:65], v[116:117] op_sel_hi:[0,1,1]
	v_cvt_pk_bf16_f32 v142, v141, v141
	v_pk_fma_f32 v[84:85], v[0:1], v[54:55], v[114:115] op_sel_hi:[0,1,1]
	global_store_short v147, v142, s[100:101]
	v_pk_fma_f32 v[118:119], v[140:141], v[58:59], v[118:119] op_sel_hi:[0,1,1]
	v_pk_fma_f32 v[86:87], v[0:1], v[56:57], v[116:117] op_sel_hi:[0,1,1]
	v_pk_fma_f32 v[120:121], v[140:141], v[60:61], v[120:121] op_sel_hi:[0,1,1]
	v_pk_fma_f32 v[88:89], v[0:1], v[42:43], v[118:119] op_sel_hi:[0,1,1]
	v_pk_fma_f32 v[90:91], v[0:1], v[44:45], v[120:121] op_sel_hi:[0,1,1]
	s_waitcnt lgkmcnt(0)
	v_pk_fma_f32 v[106:107], v[84:85], v[34:35], 0 op_sel_hi:[1,1,0]
	v_pk_fma_f32 v[108:109], v[84:85], v[22:23], 0 op_sel_hi:[1,1,0]
	ds_read_b128 v[70:73], v100 offset:7840
	ds_read_b128 v[66:69], v100 offset:7856
	v_pk_fma_f32 v[106:107], v[86:87], v[36:37], v[106:107]
	v_pk_fma_f32 v[108:109], v[86:87], v[24:25], v[108:109]
	ds_read_b128 v[50:53], v100 offset:8096
	ds_read_b128 v[46:49], v100 offset:8112
	v_pk_fma_f32 v[106:107], v[88:89], v[38:39], v[106:107]
	v_pk_fma_f32 v[108:109], v[88:89], v[18:19], v[108:109]
	ds_read_b128 v[54:57], v100 offset:8352
	ds_read_b128 v[42:45], v100 offset:8368
	v_pk_fma_f32 v[106:107], v[90:91], v[40:41], v[106:107]
	v_pk_fma_f32 v[108:109], v[90:91], v[20:21], v[108:109]
	ds_read_b128 v[78:81], v100 offset:8608
	ds_read_b128 v[74:77], v100 offset:8624
	v_add_f32_e32 v130, v106, v107
	v_add_f32_e32 v131, v108, v109
	v_pk_mul_f32 v[114:115], v[84:85], v[2:3]
	v_add_f32_dpp v130, v130, v130 quad_perm:[1,0,3,2] row_mask:0xf bank_mask:0xf bound_ctrl:1
	v_add_f32_dpp v131, v131, v131 quad_perm:[1,0,3,2] row_mask:0xf bank_mask:0xf bound_ctrl:1
	v_pk_mul_f32 v[116:117], v[86:87], v[4:5]
	v_add_f32_dpp v130, v130, v130 quad_perm:[2,3,0,1] row_mask:0xf bank_mask:0xf bound_ctrl:1
	v_add_f32_dpp v131, v131, v131 quad_perm:[2,3,0,1] row_mask:0xf bank_mask:0xf bound_ctrl:1
	v_pk_mul_f32 v[118:119], v[88:89], v[6:7]
	v_add_f32_dpp v130, v130, v130 row_half_mirror row_mask:0xf bank_mask:0xf bound_ctrl:1
	v_add_f32_dpp v131, v131, v131 row_half_mirror row_mask:0xf bank_mask:0xf bound_ctrl:1
	v_pk_mul_f32 v[120:121], v[90:91], v[8:9]
	ds_read_b128 v[62:65], v100 offset:8864
	ds_read_b128 v[58:61], v100 offset:8880
	v_mul_f32_e32 v132, v130, v96
	v_mul_f32_e32 v133, v97, v94
	ds_read_b32 v0, v101 offset:9120
	v_add_f32_e32 v131, v132, v131
	ds_read_b64 v[98:99], v1 offset:9376
	v_add_f32_e32 v131, v133, v131
	v_pk_fma_f32 v[114:115], v[130:131], v[26:27], v[114:115] op_sel_hi:[0,1,1]
	v_pk_fma_f32 v[116:117], v[130:131], v[28:29], v[116:117] op_sel_hi:[0,1,1]
	v_cvt_pk_bf16_f32 v132, v131, v131
	v_pk_fma_f32 v[84:85], v[94:95], v[10:11], v[114:115] op_sel_hi:[0,1,1]
	global_store_short v148, v132, s[100:101]
	v_pk_fma_f32 v[118:119], v[130:131], v[30:31], v[118:119] op_sel_hi:[0,1,1]
	v_pk_fma_f32 v[86:87], v[94:95], v[12:13], v[116:117] op_sel_hi:[0,1,1]
	v_pk_fma_f32 v[120:121], v[130:131], v[32:33], v[120:121] op_sel_hi:[0,1,1]
	v_pk_fma_f32 v[88:89], v[94:95], v[14:15], v[118:119] op_sel_hi:[0,1,1]
	v_pk_fma_f32 v[90:91], v[94:95], v[16:17], v[120:121] op_sel_hi:[0,1,1]
	s_waitcnt lgkmcnt(0)
	v_pk_fma_f32 v[110:111], v[84:85], v[78:79], 0 op_sel_hi:[1,1,0]
	v_pk_fma_f32 v[112:113], v[84:85], v[70:71], 0 op_sel_hi:[1,1,0]
	ds_read_b128 v[22:25], v100 offset:9408
	ds_read_b128 v[18:21], v100 offset:9424
	v_pk_fma_f32 v[110:111], v[86:87], v[80:81], v[110:111]
	v_pk_fma_f32 v[112:113], v[86:87], v[72:73], v[112:113]
	ds_read_b128 v[2:5], v100 offset:9664
	ds_read_b128 v[6:9], v100 offset:9680
	v_pk_fma_f32 v[110:111], v[88:89], v[74:75], v[110:111]
	v_pk_fma_f32 v[112:113], v[88:89], v[66:67], v[112:113]
	ds_read_b128 v[10:13], v100 offset:9920
	ds_read_b128 v[14:17], v100 offset:9936
	v_pk_fma_f32 v[110:111], v[90:91], v[76:77], v[110:111]
	v_pk_fma_f32 v[112:113], v[90:91], v[68:69], v[112:113]
	ds_read_b128 v[34:37], v100 offset:10176
	ds_read_b128 v[38:41], v100 offset:10192
	v_add_f32_e32 v140, v110, v111
	v_add_f32_e32 v141, v112, v113
	v_pk_mul_f32 v[114:115], v[84:85], v[50:51]
	v_add_f32_dpp v140, v140, v140 quad_perm:[1,0,3,2] row_mask:0xf bank_mask:0xf bound_ctrl:1
	v_add_f32_dpp v141, v141, v141 quad_perm:[1,0,3,2] row_mask:0xf bank_mask:0xf bound_ctrl:1
	v_pk_mul_f32 v[116:117], v[86:87], v[52:53]
	v_add_f32_dpp v140, v140, v140 quad_perm:[2,3,0,1] row_mask:0xf bank_mask:0xf bound_ctrl:1
	v_add_f32_dpp v141, v141, v141 quad_perm:[2,3,0,1] row_mask:0xf bank_mask:0xf bound_ctrl:1
	v_pk_mul_f32 v[118:119], v[88:89], v[46:47]
	v_add_f32_dpp v140, v140, v140 row_half_mirror row_mask:0xf bank_mask:0xf bound_ctrl:1
	v_add_f32_dpp v141, v141, v141 row_half_mirror row_mask:0xf bank_mask:0xf bound_ctrl:1
	v_pk_mul_f32 v[120:121], v[90:91], v[48:49]
	ds_read_b128 v[26:29], v100 offset:10432
	ds_read_b128 v[30:33], v100 offset:10448
	v_mul_f32_e32 v142, v140, v98
	v_mul_f32_e32 v143, v99, v0
	ds_read_b32 v94, v101 offset:10688
	v_add_f32_e32 v141, v142, v141
	ds_read_b64 v[96:97], v1 offset:10944
	v_add_f32_e32 v141, v143, v141
	v_pk_fma_f32 v[114:115], v[140:141], v[62:63], v[114:115] op_sel_hi:[0,1,1]
	v_pk_fma_f32 v[116:117], v[140:141], v[64:65], v[116:117] op_sel_hi:[0,1,1]
	v_cvt_pk_bf16_f32 v142, v141, v141
	v_pk_fma_f32 v[84:85], v[0:1], v[54:55], v[114:115] op_sel_hi:[0,1,1]
	global_store_short v149, v142, s[100:101]
	v_pk_fma_f32 v[118:119], v[140:141], v[58:59], v[118:119] op_sel_hi:[0,1,1]
	v_pk_fma_f32 v[86:87], v[0:1], v[56:57], v[116:117] op_sel_hi:[0,1,1]
	v_pk_fma_f32 v[120:121], v[140:141], v[60:61], v[120:121] op_sel_hi:[0,1,1]
	v_pk_fma_f32 v[88:89], v[0:1], v[42:43], v[118:119] op_sel_hi:[0,1,1]
	v_pk_fma_f32 v[90:91], v[0:1], v[44:45], v[120:121] op_sel_hi:[0,1,1]
	s_waitcnt lgkmcnt(0)
	v_pk_fma_f32 v[106:107], v[84:85], v[34:35], 0 op_sel_hi:[1,1,0]
	v_pk_fma_f32 v[108:109], v[84:85], v[22:23], 0 op_sel_hi:[1,1,0]
	ds_read_b128 v[70:73], v100 offset:10976
	ds_read_b128 v[66:69], v100 offset:10992
	v_pk_fma_f32 v[106:107], v[86:87], v[36:37], v[106:107]
	v_pk_fma_f32 v[108:109], v[86:87], v[24:25], v[108:109]
	ds_read_b128 v[50:53], v100 offset:11232
	ds_read_b128 v[46:49], v100 offset:11248
	v_pk_fma_f32 v[106:107], v[88:89], v[38:39], v[106:107]
	v_pk_fma_f32 v[108:109], v[88:89], v[18:19], v[108:109]
	ds_read_b128 v[54:57], v100 offset:11488
	ds_read_b128 v[42:45], v100 offset:11504
	v_pk_fma_f32 v[106:107], v[90:91], v[40:41], v[106:107]
	v_pk_fma_f32 v[108:109], v[90:91], v[20:21], v[108:109]
	ds_read_b128 v[78:81], v100 offset:11744
	ds_read_b128 v[74:77], v100 offset:11760
	v_add_f32_e32 v130, v106, v107
	v_add_f32_e32 v131, v108, v109
	v_pk_mul_f32 v[114:115], v[84:85], v[2:3]
	v_add_f32_dpp v130, v130, v130 quad_perm:[1,0,3,2] row_mask:0xf bank_mask:0xf bound_ctrl:1
	v_add_f32_dpp v131, v131, v131 quad_perm:[1,0,3,2] row_mask:0xf bank_mask:0xf bound_ctrl:1
	v_pk_mul_f32 v[116:117], v[86:87], v[4:5]
	v_add_f32_dpp v130, v130, v130 quad_perm:[2,3,0,1] row_mask:0xf bank_mask:0xf bound_ctrl:1
	v_add_f32_dpp v131, v131, v131 quad_perm:[2,3,0,1] row_mask:0xf bank_mask:0xf bound_ctrl:1
	v_pk_mul_f32 v[118:119], v[88:89], v[6:7]
	v_add_f32_dpp v130, v130, v130 row_half_mirror row_mask:0xf bank_mask:0xf bound_ctrl:1
	v_add_f32_dpp v131, v131, v131 row_half_mirror row_mask:0xf bank_mask:0xf bound_ctrl:1
	v_pk_mul_f32 v[120:121], v[90:91], v[8:9]
	ds_read_b128 v[62:65], v100 offset:12000
	ds_read_b128 v[58:61], v100 offset:12016
	v_mul_f32_e32 v132, v130, v96
	v_mul_f32_e32 v133, v97, v94
	ds_read_b32 v0, v101 offset:12256
	v_add_f32_e32 v131, v132, v131
	ds_read_b64 v[98:99], v1 offset:12512
	v_add_f32_e32 v131, v133, v131
	v_pk_fma_f32 v[114:115], v[130:131], v[26:27], v[114:115] op_sel_hi:[0,1,1]
	v_pk_fma_f32 v[116:117], v[130:131], v[28:29], v[116:117] op_sel_hi:[0,1,1]
	v_cvt_pk_bf16_f32 v132, v131, v131
	v_pk_fma_f32 v[84:85], v[94:95], v[10:11], v[114:115] op_sel_hi:[0,1,1]
	global_store_short v150, v132, s[100:101]
	v_pk_fma_f32 v[118:119], v[130:131], v[30:31], v[118:119] op_sel_hi:[0,1,1]
	v_pk_fma_f32 v[86:87], v[94:95], v[12:13], v[116:117] op_sel_hi:[0,1,1]
	v_pk_fma_f32 v[120:121], v[130:131], v[32:33], v[120:121] op_sel_hi:[0,1,1]
	v_pk_fma_f32 v[88:89], v[94:95], v[14:15], v[118:119] op_sel_hi:[0,1,1]
	v_pk_fma_f32 v[90:91], v[94:95], v[16:17], v[120:121] op_sel_hi:[0,1,1]
	s_waitcnt lgkmcnt(0)
	v_pk_fma_f32 v[110:111], v[84:85], v[78:79], 0 op_sel_hi:[1,1,0]
	v_pk_fma_f32 v[112:113], v[84:85], v[70:71], 0 op_sel_hi:[1,1,0]
	ds_read_b128 v[22:25], v100 offset:12544
	ds_read_b128 v[18:21], v100 offset:12560
	v_pk_fma_f32 v[110:111], v[86:87], v[80:81], v[110:111]
	v_pk_fma_f32 v[112:113], v[86:87], v[72:73], v[112:113]
	ds_read_b128 v[2:5], v100 offset:12800
	ds_read_b128 v[6:9], v100 offset:12816
	v_pk_fma_f32 v[110:111], v[88:89], v[74:75], v[110:111]
	v_pk_fma_f32 v[112:113], v[88:89], v[66:67], v[112:113]
	ds_read_b128 v[10:13], v100 offset:13056
	ds_read_b128 v[14:17], v100 offset:13072
	v_pk_fma_f32 v[110:111], v[90:91], v[76:77], v[110:111]
	v_pk_fma_f32 v[112:113], v[90:91], v[68:69], v[112:113]
	ds_read_b128 v[34:37], v100 offset:13312
	ds_read_b128 v[38:41], v100 offset:13328
	v_add_f32_e32 v140, v110, v111
	v_add_f32_e32 v141, v112, v113
	v_pk_mul_f32 v[114:115], v[84:85], v[50:51]
	v_add_f32_dpp v140, v140, v140 quad_perm:[1,0,3,2] row_mask:0xf bank_mask:0xf bound_ctrl:1
	v_add_f32_dpp v141, v141, v141 quad_perm:[1,0,3,2] row_mask:0xf bank_mask:0xf bound_ctrl:1
	v_pk_mul_f32 v[116:117], v[86:87], v[52:53]
	v_add_f32_dpp v140, v140, v140 quad_perm:[2,3,0,1] row_mask:0xf bank_mask:0xf bound_ctrl:1
	v_add_f32_dpp v141, v141, v141 quad_perm:[2,3,0,1] row_mask:0xf bank_mask:0xf bound_ctrl:1
	v_pk_mul_f32 v[118:119], v[88:89], v[46:47]
	v_add_f32_dpp v140, v140, v140 row_half_mirror row_mask:0xf bank_mask:0xf bound_ctrl:1
	v_add_f32_dpp v141, v141, v141 row_half_mirror row_mask:0xf bank_mask:0xf bound_ctrl:1
	v_pk_mul_f32 v[120:121], v[90:91], v[48:49]
	ds_read_b128 v[26:29], v100 offset:13568
	ds_read_b128 v[30:33], v100 offset:13584
	v_mul_f32_e32 v142, v140, v98
	v_mul_f32_e32 v143, v99, v0
	ds_read_b32 v94, v101 offset:13824
	v_add_f32_e32 v141, v142, v141
	ds_read_b64 v[96:97], v1 offset:14080
	v_add_f32_e32 v141, v143, v141
	v_pk_fma_f32 v[114:115], v[140:141], v[62:63], v[114:115] op_sel_hi:[0,1,1]
	v_pk_fma_f32 v[116:117], v[140:141], v[64:65], v[116:117] op_sel_hi:[0,1,1]
	v_cvt_pk_bf16_f32 v142, v141, v141
	v_pk_fma_f32 v[84:85], v[0:1], v[54:55], v[114:115] op_sel_hi:[0,1,1]
	global_store_short v151, v142, s[100:101]
	v_pk_fma_f32 v[118:119], v[140:141], v[58:59], v[118:119] op_sel_hi:[0,1,1]
	v_pk_fma_f32 v[86:87], v[0:1], v[56:57], v[116:117] op_sel_hi:[0,1,1]
	v_pk_fma_f32 v[120:121], v[140:141], v[60:61], v[120:121] op_sel_hi:[0,1,1]
	v_pk_fma_f32 v[88:89], v[0:1], v[42:43], v[118:119] op_sel_hi:[0,1,1]
	v_pk_fma_f32 v[90:91], v[0:1], v[44:45], v[120:121] op_sel_hi:[0,1,1]
	s_waitcnt lgkmcnt(0)
	v_pk_fma_f32 v[106:107], v[84:85], v[34:35], 0 op_sel_hi:[1,1,0]
	v_pk_fma_f32 v[108:109], v[84:85], v[22:23], 0 op_sel_hi:[1,1,0]
	ds_read_b128 v[70:73], v100 offset:14112
	ds_read_b128 v[66:69], v100 offset:14128
	v_pk_fma_f32 v[106:107], v[86:87], v[36:37], v[106:107]
	v_pk_fma_f32 v[108:109], v[86:87], v[24:25], v[108:109]
	ds_read_b128 v[50:53], v100 offset:14368
	ds_read_b128 v[46:49], v100 offset:14384
	v_pk_fma_f32 v[106:107], v[88:89], v[38:39], v[106:107]
	v_pk_fma_f32 v[108:109], v[88:89], v[18:19], v[108:109]
	ds_read_b128 v[54:57], v100 offset:14624
	ds_read_b128 v[42:45], v100 offset:14640
	v_pk_fma_f32 v[106:107], v[90:91], v[40:41], v[106:107]
	v_pk_fma_f32 v[108:109], v[90:91], v[20:21], v[108:109]
	ds_read_b128 v[78:81], v100 offset:14880
	ds_read_b128 v[74:77], v100 offset:14896
	v_add_f32_e32 v130, v106, v107
	v_add_f32_e32 v131, v108, v109
	v_pk_mul_f32 v[114:115], v[84:85], v[2:3]
	v_add_f32_dpp v130, v130, v130 quad_perm:[1,0,3,2] row_mask:0xf bank_mask:0xf bound_ctrl:1
	v_add_f32_dpp v131, v131, v131 quad_perm:[1,0,3,2] row_mask:0xf bank_mask:0xf bound_ctrl:1
	v_pk_mul_f32 v[116:117], v[86:87], v[4:5]
	v_add_f32_dpp v130, v130, v130 quad_perm:[2,3,0,1] row_mask:0xf bank_mask:0xf bound_ctrl:1
	v_add_f32_dpp v131, v131, v131 quad_perm:[2,3,0,1] row_mask:0xf bank_mask:0xf bound_ctrl:1
	v_pk_mul_f32 v[118:119], v[88:89], v[6:7]
	v_add_f32_dpp v130, v130, v130 row_half_mirror row_mask:0xf bank_mask:0xf bound_ctrl:1
	v_add_f32_dpp v131, v131, v131 row_half_mirror row_mask:0xf bank_mask:0xf bound_ctrl:1
	v_pk_mul_f32 v[120:121], v[90:91], v[8:9]
	ds_read_b128 v[62:65], v100 offset:15136
	ds_read_b128 v[58:61], v100 offset:15152
	v_mul_f32_e32 v132, v130, v96
	v_mul_f32_e32 v133, v97, v94
	ds_read_b32 v0, v101 offset:15392
	v_add_f32_e32 v131, v132, v131
	ds_read_b64 v[98:99], v1 offset:15648
	v_add_f32_e32 v131, v133, v131
	v_pk_fma_f32 v[114:115], v[130:131], v[26:27], v[114:115] op_sel_hi:[0,1,1]
	v_pk_fma_f32 v[116:117], v[130:131], v[28:29], v[116:117] op_sel_hi:[0,1,1]
	v_cvt_pk_bf16_f32 v132, v131, v131
	v_pk_fma_f32 v[84:85], v[94:95], v[10:11], v[114:115] op_sel_hi:[0,1,1]
	global_store_short v152, v132, s[100:101]
	v_pk_fma_f32 v[118:119], v[130:131], v[30:31], v[118:119] op_sel_hi:[0,1,1]
	v_pk_fma_f32 v[86:87], v[94:95], v[12:13], v[116:117] op_sel_hi:[0,1,1]
	v_pk_fma_f32 v[120:121], v[130:131], v[32:33], v[120:121] op_sel_hi:[0,1,1]
	v_pk_fma_f32 v[88:89], v[94:95], v[14:15], v[118:119] op_sel_hi:[0,1,1]
	v_pk_fma_f32 v[90:91], v[94:95], v[16:17], v[120:121] op_sel_hi:[0,1,1]
	s_waitcnt lgkmcnt(0)
	v_pk_fma_f32 v[110:111], v[84:85], v[78:79], 0 op_sel_hi:[1,1,0]
	v_pk_fma_f32 v[112:113], v[84:85], v[70:71], 0 op_sel_hi:[1,1,0]
	ds_read_b128 v[22:25], v100 offset:15680
	ds_read_b128 v[18:21], v100 offset:15696
	v_pk_fma_f32 v[110:111], v[86:87], v[80:81], v[110:111]
	v_pk_fma_f32 v[112:113], v[86:87], v[72:73], v[112:113]
	ds_read_b128 v[2:5], v100 offset:15936
	ds_read_b128 v[6:9], v100 offset:15952
	v_pk_fma_f32 v[110:111], v[88:89], v[74:75], v[110:111]
	v_pk_fma_f32 v[112:113], v[88:89], v[66:67], v[112:113]
	ds_read_b128 v[10:13], v100 offset:16192
	ds_read_b128 v[14:17], v100 offset:16208
	v_pk_fma_f32 v[110:111], v[90:91], v[76:77], v[110:111]
	v_pk_fma_f32 v[112:113], v[90:91], v[68:69], v[112:113]
	ds_read_b128 v[34:37], v100 offset:16448
	ds_read_b128 v[38:41], v100 offset:16464
	v_add_f32_e32 v140, v110, v111
	v_add_f32_e32 v141, v112, v113
	v_pk_mul_f32 v[114:115], v[84:85], v[50:51]
	v_add_f32_dpp v140, v140, v140 quad_perm:[1,0,3,2] row_mask:0xf bank_mask:0xf bound_ctrl:1
	v_add_f32_dpp v141, v141, v141 quad_perm:[1,0,3,2] row_mask:0xf bank_mask:0xf bound_ctrl:1
	v_pk_mul_f32 v[116:117], v[86:87], v[52:53]
	v_add_f32_dpp v140, v140, v140 quad_perm:[2,3,0,1] row_mask:0xf bank_mask:0xf bound_ctrl:1
	v_add_f32_dpp v141, v141, v141 quad_perm:[2,3,0,1] row_mask:0xf bank_mask:0xf bound_ctrl:1
	v_pk_mul_f32 v[118:119], v[88:89], v[46:47]
	v_add_f32_dpp v140, v140, v140 row_half_mirror row_mask:0xf bank_mask:0xf bound_ctrl:1
	v_add_f32_dpp v141, v141, v141 row_half_mirror row_mask:0xf bank_mask:0xf bound_ctrl:1
	v_pk_mul_f32 v[120:121], v[90:91], v[48:49]
	ds_read_b128 v[26:29], v100 offset:16704
	ds_read_b128 v[30:33], v100 offset:16720
	v_mul_f32_e32 v142, v140, v98
	v_mul_f32_e32 v143, v99, v0
	ds_read_b32 v94, v101 offset:16960
	v_add_f32_e32 v141, v142, v141
	ds_read_b64 v[96:97], v1 offset:17216
	v_add_f32_e32 v141, v143, v141
	v_pk_fma_f32 v[114:115], v[140:141], v[62:63], v[114:115] op_sel_hi:[0,1,1]
	v_pk_fma_f32 v[116:117], v[140:141], v[64:65], v[116:117] op_sel_hi:[0,1,1]
	v_cvt_pk_bf16_f32 v142, v141, v141
	v_pk_fma_f32 v[84:85], v[0:1], v[54:55], v[114:115] op_sel_hi:[0,1,1]
	global_store_short v153, v142, s[100:101]
	v_pk_fma_f32 v[118:119], v[140:141], v[58:59], v[118:119] op_sel_hi:[0,1,1]
	v_pk_fma_f32 v[86:87], v[0:1], v[56:57], v[116:117] op_sel_hi:[0,1,1]
	v_pk_fma_f32 v[120:121], v[140:141], v[60:61], v[120:121] op_sel_hi:[0,1,1]
	v_pk_fma_f32 v[88:89], v[0:1], v[42:43], v[118:119] op_sel_hi:[0,1,1]
	v_pk_fma_f32 v[90:91], v[0:1], v[44:45], v[120:121] op_sel_hi:[0,1,1]
	s_waitcnt lgkmcnt(0)
	v_pk_fma_f32 v[106:107], v[84:85], v[34:35], 0 op_sel_hi:[1,1,0]
	v_pk_fma_f32 v[108:109], v[84:85], v[22:23], 0 op_sel_hi:[1,1,0]
	ds_read_b128 v[70:73], v100 offset:17248
	ds_read_b128 v[66:69], v100 offset:17264
	v_pk_fma_f32 v[106:107], v[86:87], v[36:37], v[106:107]
	v_pk_fma_f32 v[108:109], v[86:87], v[24:25], v[108:109]
	ds_read_b128 v[50:53], v100 offset:17504
	ds_read_b128 v[46:49], v100 offset:17520
	v_pk_fma_f32 v[106:107], v[88:89], v[38:39], v[106:107]
	v_pk_fma_f32 v[108:109], v[88:89], v[18:19], v[108:109]
	ds_read_b128 v[54:57], v100 offset:17760
	ds_read_b128 v[42:45], v100 offset:17776
	v_pk_fma_f32 v[106:107], v[90:91], v[40:41], v[106:107]
	v_pk_fma_f32 v[108:109], v[90:91], v[20:21], v[108:109]
	ds_read_b128 v[78:81], v100 offset:18016
	ds_read_b128 v[74:77], v100 offset:18032
	v_add_f32_e32 v130, v106, v107
	v_add_f32_e32 v131, v108, v109
	v_pk_mul_f32 v[114:115], v[84:85], v[2:3]
	v_add_f32_dpp v130, v130, v130 quad_perm:[1,0,3,2] row_mask:0xf bank_mask:0xf bound_ctrl:1
	v_add_f32_dpp v131, v131, v131 quad_perm:[1,0,3,2] row_mask:0xf bank_mask:0xf bound_ctrl:1
	v_pk_mul_f32 v[116:117], v[86:87], v[4:5]
	v_add_f32_dpp v130, v130, v130 quad_perm:[2,3,0,1] row_mask:0xf bank_mask:0xf bound_ctrl:1
	v_add_f32_dpp v131, v131, v131 quad_perm:[2,3,0,1] row_mask:0xf bank_mask:0xf bound_ctrl:1
	v_pk_mul_f32 v[118:119], v[88:89], v[6:7]
	v_add_f32_dpp v130, v130, v130 row_half_mirror row_mask:0xf bank_mask:0xf bound_ctrl:1
	v_add_f32_dpp v131, v131, v131 row_half_mirror row_mask:0xf bank_mask:0xf bound_ctrl:1
	v_pk_mul_f32 v[120:121], v[90:91], v[8:9]
	ds_read_b128 v[62:65], v100 offset:18272
	ds_read_b128 v[58:61], v100 offset:18288
	v_mul_f32_e32 v132, v130, v96
	v_mul_f32_e32 v133, v97, v94
	ds_read_b32 v0, v101 offset:18528
	v_add_f32_e32 v131, v132, v131
	ds_read_b64 v[98:99], v1 offset:18784
	v_add_f32_e32 v131, v133, v131
	v_pk_fma_f32 v[114:115], v[130:131], v[26:27], v[114:115] op_sel_hi:[0,1,1]
	v_pk_fma_f32 v[116:117], v[130:131], v[28:29], v[116:117] op_sel_hi:[0,1,1]
	v_cvt_pk_bf16_f32 v132, v131, v131
	v_pk_fma_f32 v[84:85], v[94:95], v[10:11], v[114:115] op_sel_hi:[0,1,1]
	global_store_short v154, v132, s[100:101]
	v_pk_fma_f32 v[118:119], v[130:131], v[30:31], v[118:119] op_sel_hi:[0,1,1]
	v_pk_fma_f32 v[86:87], v[94:95], v[12:13], v[116:117] op_sel_hi:[0,1,1]
	v_pk_fma_f32 v[120:121], v[130:131], v[32:33], v[120:121] op_sel_hi:[0,1,1]
	v_pk_fma_f32 v[88:89], v[94:95], v[14:15], v[118:119] op_sel_hi:[0,1,1]
	v_pk_fma_f32 v[90:91], v[94:95], v[16:17], v[120:121] op_sel_hi:[0,1,1]
	s_waitcnt lgkmcnt(0)
	v_pk_fma_f32 v[110:111], v[84:85], v[78:79], 0 op_sel_hi:[1,1,0]
	v_pk_fma_f32 v[112:113], v[84:85], v[70:71], 0 op_sel_hi:[1,1,0]
	ds_read_b128 v[22:25], v100 offset:18816
	ds_read_b128 v[18:21], v100 offset:18832
	v_pk_fma_f32 v[110:111], v[86:87], v[80:81], v[110:111]
	v_pk_fma_f32 v[112:113], v[86:87], v[72:73], v[112:113]
	ds_read_b128 v[2:5], v100 offset:19072
	ds_read_b128 v[6:9], v100 offset:19088
	v_pk_fma_f32 v[110:111], v[88:89], v[74:75], v[110:111]
	v_pk_fma_f32 v[112:113], v[88:89], v[66:67], v[112:113]
	ds_read_b128 v[10:13], v100 offset:19328
	ds_read_b128 v[14:17], v100 offset:19344
	v_pk_fma_f32 v[110:111], v[90:91], v[76:77], v[110:111]
	v_pk_fma_f32 v[112:113], v[90:91], v[68:69], v[112:113]
	ds_read_b128 v[34:37], v100 offset:19584
	ds_read_b128 v[38:41], v100 offset:19600
	v_add_f32_e32 v140, v110, v111
	v_add_f32_e32 v141, v112, v113
	v_pk_mul_f32 v[114:115], v[84:85], v[50:51]
	v_add_f32_dpp v140, v140, v140 quad_perm:[1,0,3,2] row_mask:0xf bank_mask:0xf bound_ctrl:1
	v_add_f32_dpp v141, v141, v141 quad_perm:[1,0,3,2] row_mask:0xf bank_mask:0xf bound_ctrl:1
	v_pk_mul_f32 v[116:117], v[86:87], v[52:53]
	v_add_f32_dpp v140, v140, v140 quad_perm:[2,3,0,1] row_mask:0xf bank_mask:0xf bound_ctrl:1
	v_add_f32_dpp v141, v141, v141 quad_perm:[2,3,0,1] row_mask:0xf bank_mask:0xf bound_ctrl:1
	v_pk_mul_f32 v[118:119], v[88:89], v[46:47]
	v_add_f32_dpp v140, v140, v140 row_half_mirror row_mask:0xf bank_mask:0xf bound_ctrl:1
	v_add_f32_dpp v141, v141, v141 row_half_mirror row_mask:0xf bank_mask:0xf bound_ctrl:1
	v_pk_mul_f32 v[120:121], v[90:91], v[48:49]
	ds_read_b128 v[26:29], v100 offset:19840
	ds_read_b128 v[30:33], v100 offset:19856
	v_mul_f32_e32 v142, v140, v98
	v_mul_f32_e32 v143, v99, v0
	ds_read_b32 v94, v101 offset:20096
	v_add_f32_e32 v141, v142, v141
	ds_read_b64 v[96:97], v1 offset:20352
	v_add_f32_e32 v141, v143, v141
	v_pk_fma_f32 v[114:115], v[140:141], v[62:63], v[114:115] op_sel_hi:[0,1,1]
	v_pk_fma_f32 v[116:117], v[140:141], v[64:65], v[116:117] op_sel_hi:[0,1,1]
	v_cvt_pk_bf16_f32 v142, v141, v141
	v_pk_fma_f32 v[84:85], v[0:1], v[54:55], v[114:115] op_sel_hi:[0,1,1]
	global_store_short v155, v142, s[100:101]
	v_pk_fma_f32 v[118:119], v[140:141], v[58:59], v[118:119] op_sel_hi:[0,1,1]
	v_pk_fma_f32 v[86:87], v[0:1], v[56:57], v[116:117] op_sel_hi:[0,1,1]
	v_pk_fma_f32 v[120:121], v[140:141], v[60:61], v[120:121] op_sel_hi:[0,1,1]
	v_pk_fma_f32 v[88:89], v[0:1], v[42:43], v[118:119] op_sel_hi:[0,1,1]
	v_pk_fma_f32 v[90:91], v[0:1], v[44:45], v[120:121] op_sel_hi:[0,1,1]
	s_waitcnt lgkmcnt(0)
	v_pk_fma_f32 v[106:107], v[84:85], v[34:35], 0 op_sel_hi:[1,1,0]
	v_pk_fma_f32 v[108:109], v[84:85], v[22:23], 0 op_sel_hi:[1,1,0]
	ds_read_b128 v[70:73], v100 offset:20384
	ds_read_b128 v[66:69], v100 offset:20400
	v_pk_fma_f32 v[106:107], v[86:87], v[36:37], v[106:107]
	v_pk_fma_f32 v[108:109], v[86:87], v[24:25], v[108:109]
	ds_read_b128 v[50:53], v100 offset:20640
	ds_read_b128 v[46:49], v100 offset:20656
	v_pk_fma_f32 v[106:107], v[88:89], v[38:39], v[106:107]
	v_pk_fma_f32 v[108:109], v[88:89], v[18:19], v[108:109]
	ds_read_b128 v[54:57], v100 offset:20896
	ds_read_b128 v[42:45], v100 offset:20912
	v_pk_fma_f32 v[106:107], v[90:91], v[40:41], v[106:107]
	v_pk_fma_f32 v[108:109], v[90:91], v[20:21], v[108:109]
	ds_read_b128 v[78:81], v100 offset:21152
	ds_read_b128 v[74:77], v100 offset:21168
	v_add_f32_e32 v130, v106, v107
	v_add_f32_e32 v131, v108, v109
	v_pk_mul_f32 v[114:115], v[84:85], v[2:3]
	v_add_f32_dpp v130, v130, v130 quad_perm:[1,0,3,2] row_mask:0xf bank_mask:0xf bound_ctrl:1
	v_add_f32_dpp v131, v131, v131 quad_perm:[1,0,3,2] row_mask:0xf bank_mask:0xf bound_ctrl:1
	v_pk_mul_f32 v[116:117], v[86:87], v[4:5]
	v_add_f32_dpp v130, v130, v130 quad_perm:[2,3,0,1] row_mask:0xf bank_mask:0xf bound_ctrl:1
	v_add_f32_dpp v131, v131, v131 quad_perm:[2,3,0,1] row_mask:0xf bank_mask:0xf bound_ctrl:1
	v_pk_mul_f32 v[118:119], v[88:89], v[6:7]
	v_add_f32_dpp v130, v130, v130 row_half_mirror row_mask:0xf bank_mask:0xf bound_ctrl:1
	v_add_f32_dpp v131, v131, v131 row_half_mirror row_mask:0xf bank_mask:0xf bound_ctrl:1
	v_pk_mul_f32 v[120:121], v[90:91], v[8:9]
	ds_read_b128 v[62:65], v100 offset:21408
	ds_read_b128 v[58:61], v100 offset:21424
	v_mul_f32_e32 v132, v130, v96
	v_mul_f32_e32 v133, v97, v94
	ds_read_b32 v0, v101 offset:21664
	v_add_f32_e32 v131, v132, v131
	ds_read_b64 v[98:99], v1 offset:21920
	v_add_f32_e32 v131, v133, v131
	v_pk_fma_f32 v[114:115], v[130:131], v[26:27], v[114:115] op_sel_hi:[0,1,1]
	v_pk_fma_f32 v[116:117], v[130:131], v[28:29], v[116:117] op_sel_hi:[0,1,1]
	v_cvt_pk_bf16_f32 v132, v131, v131
	v_pk_fma_f32 v[84:85], v[94:95], v[10:11], v[114:115] op_sel_hi:[0,1,1]
	global_store_short v156, v132, s[100:101]
	v_pk_fma_f32 v[118:119], v[130:131], v[30:31], v[118:119] op_sel_hi:[0,1,1]
	v_pk_fma_f32 v[86:87], v[94:95], v[12:13], v[116:117] op_sel_hi:[0,1,1]
	v_pk_fma_f32 v[120:121], v[130:131], v[32:33], v[120:121] op_sel_hi:[0,1,1]
	v_pk_fma_f32 v[88:89], v[94:95], v[14:15], v[118:119] op_sel_hi:[0,1,1]
	v_pk_fma_f32 v[90:91], v[94:95], v[16:17], v[120:121] op_sel_hi:[0,1,1]
	s_waitcnt lgkmcnt(0)
	v_pk_fma_f32 v[110:111], v[84:85], v[78:79], 0 op_sel_hi:[1,1,0]
	v_pk_fma_f32 v[112:113], v[84:85], v[70:71], 0 op_sel_hi:[1,1,0]
	ds_read_b128 v[22:25], v100 offset:21952
	ds_read_b128 v[18:21], v100 offset:21968
	v_pk_fma_f32 v[110:111], v[86:87], v[80:81], v[110:111]
	v_pk_fma_f32 v[112:113], v[86:87], v[72:73], v[112:113]
	ds_read_b128 v[2:5], v100 offset:22208
	ds_read_b128 v[6:9], v100 offset:22224
	v_pk_fma_f32 v[110:111], v[88:89], v[74:75], v[110:111]
	v_pk_fma_f32 v[112:113], v[88:89], v[66:67], v[112:113]
	ds_read_b128 v[10:13], v100 offset:22464
	ds_read_b128 v[14:17], v100 offset:22480
	v_pk_fma_f32 v[110:111], v[90:91], v[76:77], v[110:111]
	v_pk_fma_f32 v[112:113], v[90:91], v[68:69], v[112:113]
	ds_read_b128 v[34:37], v100 offset:22720
	ds_read_b128 v[38:41], v100 offset:22736
	v_add_f32_e32 v140, v110, v111
	v_add_f32_e32 v141, v112, v113
	v_pk_mul_f32 v[114:115], v[84:85], v[50:51]
	v_add_f32_dpp v140, v140, v140 quad_perm:[1,0,3,2] row_mask:0xf bank_mask:0xf bound_ctrl:1
	v_add_f32_dpp v141, v141, v141 quad_perm:[1,0,3,2] row_mask:0xf bank_mask:0xf bound_ctrl:1
	v_pk_mul_f32 v[116:117], v[86:87], v[52:53]
	v_add_f32_dpp v140, v140, v140 quad_perm:[2,3,0,1] row_mask:0xf bank_mask:0xf bound_ctrl:1
	v_add_f32_dpp v141, v141, v141 quad_perm:[2,3,0,1] row_mask:0xf bank_mask:0xf bound_ctrl:1
	v_pk_mul_f32 v[118:119], v[88:89], v[46:47]
	v_add_f32_dpp v140, v140, v140 row_half_mirror row_mask:0xf bank_mask:0xf bound_ctrl:1
	v_add_f32_dpp v141, v141, v141 row_half_mirror row_mask:0xf bank_mask:0xf bound_ctrl:1
	v_pk_mul_f32 v[120:121], v[90:91], v[48:49]
	ds_read_b128 v[26:29], v100 offset:22976
	ds_read_b128 v[30:33], v100 offset:22992
	v_mul_f32_e32 v142, v140, v98
	v_mul_f32_e32 v143, v99, v0
	ds_read_b32 v94, v101 offset:23232
	v_add_f32_e32 v141, v142, v141
	ds_read_b64 v[96:97], v1 offset:23488
	v_add_f32_e32 v141, v143, v141
	v_pk_fma_f32 v[114:115], v[140:141], v[62:63], v[114:115] op_sel_hi:[0,1,1]
	v_pk_fma_f32 v[116:117], v[140:141], v[64:65], v[116:117] op_sel_hi:[0,1,1]
	v_cvt_pk_bf16_f32 v142, v141, v141
	v_pk_fma_f32 v[84:85], v[0:1], v[54:55], v[114:115] op_sel_hi:[0,1,1]
	global_store_short v157, v142, s[100:101]
	v_pk_fma_f32 v[118:119], v[140:141], v[58:59], v[118:119] op_sel_hi:[0,1,1]
	v_pk_fma_f32 v[86:87], v[0:1], v[56:57], v[116:117] op_sel_hi:[0,1,1]
	v_pk_fma_f32 v[120:121], v[140:141], v[60:61], v[120:121] op_sel_hi:[0,1,1]
	v_pk_fma_f32 v[88:89], v[0:1], v[42:43], v[118:119] op_sel_hi:[0,1,1]
	v_pk_fma_f32 v[90:91], v[0:1], v[44:45], v[120:121] op_sel_hi:[0,1,1]
	s_waitcnt lgkmcnt(0)
	v_pk_fma_f32 v[106:107], v[84:85], v[34:35], 0 op_sel_hi:[1,1,0]
	v_pk_fma_f32 v[108:109], v[84:85], v[22:23], 0 op_sel_hi:[1,1,0]
	ds_read_b128 v[70:73], v100 offset:23520
	ds_read_b128 v[66:69], v100 offset:23536
	v_pk_fma_f32 v[106:107], v[86:87], v[36:37], v[106:107]
	v_pk_fma_f32 v[108:109], v[86:87], v[24:25], v[108:109]
	ds_read_b128 v[50:53], v100 offset:23776
	ds_read_b128 v[46:49], v100 offset:23792
	v_pk_fma_f32 v[106:107], v[88:89], v[38:39], v[106:107]
	v_pk_fma_f32 v[108:109], v[88:89], v[18:19], v[108:109]
	ds_read_b128 v[54:57], v100 offset:24032
	ds_read_b128 v[42:45], v100 offset:24048
	v_pk_fma_f32 v[106:107], v[90:91], v[40:41], v[106:107]
	v_pk_fma_f32 v[108:109], v[90:91], v[20:21], v[108:109]
	ds_read_b128 v[78:81], v100 offset:24288
	ds_read_b128 v[74:77], v100 offset:24304
	v_add_f32_e32 v130, v106, v107
	v_add_f32_e32 v131, v108, v109
	v_pk_mul_f32 v[114:115], v[84:85], v[2:3]
	v_add_f32_dpp v130, v130, v130 quad_perm:[1,0,3,2] row_mask:0xf bank_mask:0xf bound_ctrl:1
	v_add_f32_dpp v131, v131, v131 quad_perm:[1,0,3,2] row_mask:0xf bank_mask:0xf bound_ctrl:1
	v_pk_mul_f32 v[116:117], v[86:87], v[4:5]
	v_add_f32_dpp v130, v130, v130 quad_perm:[2,3,0,1] row_mask:0xf bank_mask:0xf bound_ctrl:1
	v_add_f32_dpp v131, v131, v131 quad_perm:[2,3,0,1] row_mask:0xf bank_mask:0xf bound_ctrl:1
	v_pk_mul_f32 v[118:119], v[88:89], v[6:7]
	v_add_f32_dpp v130, v130, v130 row_half_mirror row_mask:0xf bank_mask:0xf bound_ctrl:1
	v_add_f32_dpp v131, v131, v131 row_half_mirror row_mask:0xf bank_mask:0xf bound_ctrl:1
	v_pk_mul_f32 v[120:121], v[90:91], v[8:9]
	ds_read_b128 v[62:65], v100 offset:24544
	ds_read_b128 v[58:61], v100 offset:24560
	v_mul_f32_e32 v132, v130, v96
	v_mul_f32_e32 v133, v97, v94
	ds_read_b32 v0, v101 offset:24800
	v_add_f32_e32 v131, v132, v131
	ds_read_b64 v[98:99], v1 offset:25056
	v_add_f32_e32 v131, v133, v131
	v_pk_fma_f32 v[114:115], v[130:131], v[26:27], v[114:115] op_sel_hi:[0,1,1]
	v_pk_fma_f32 v[116:117], v[130:131], v[28:29], v[116:117] op_sel_hi:[0,1,1]
	v_cvt_pk_bf16_f32 v132, v131, v131
	v_pk_fma_f32 v[84:85], v[94:95], v[10:11], v[114:115] op_sel_hi:[0,1,1]
	global_store_short v158, v132, s[100:101]
	v_pk_fma_f32 v[118:119], v[130:131], v[30:31], v[118:119] op_sel_hi:[0,1,1]
	v_pk_fma_f32 v[86:87], v[94:95], v[12:13], v[116:117] op_sel_hi:[0,1,1]
	v_pk_fma_f32 v[120:121], v[130:131], v[32:33], v[120:121] op_sel_hi:[0,1,1]
	v_pk_fma_f32 v[88:89], v[94:95], v[14:15], v[118:119] op_sel_hi:[0,1,1]
	v_pk_fma_f32 v[90:91], v[94:95], v[16:17], v[120:121] op_sel_hi:[0,1,1]
	s_waitcnt lgkmcnt(0)
	v_pk_fma_f32 v[110:111], v[84:85], v[78:79], 0 op_sel_hi:[1,1,0]
	v_pk_fma_f32 v[112:113], v[84:85], v[70:71], 0 op_sel_hi:[1,1,0]
	ds_read_b128 v[22:25], v100 offset:25088
	ds_read_b128 v[18:21], v100 offset:25104
	v_pk_fma_f32 v[110:111], v[86:87], v[80:81], v[110:111]
	v_pk_fma_f32 v[112:113], v[86:87], v[72:73], v[112:113]
	ds_read_b128 v[2:5], v100 offset:25344
	ds_read_b128 v[6:9], v100 offset:25360
	v_pk_fma_f32 v[110:111], v[88:89], v[74:75], v[110:111]
	v_pk_fma_f32 v[112:113], v[88:89], v[66:67], v[112:113]
	ds_read_b128 v[10:13], v100 offset:25600
	ds_read_b128 v[14:17], v100 offset:25616
	v_pk_fma_f32 v[110:111], v[90:91], v[76:77], v[110:111]
	v_pk_fma_f32 v[112:113], v[90:91], v[68:69], v[112:113]
	ds_read_b128 v[34:37], v100 offset:25856
	ds_read_b128 v[38:41], v100 offset:25872
	v_add_f32_e32 v140, v110, v111
	v_add_f32_e32 v141, v112, v113
	v_pk_mul_f32 v[114:115], v[84:85], v[50:51]
	v_add_f32_dpp v140, v140, v140 quad_perm:[1,0,3,2] row_mask:0xf bank_mask:0xf bound_ctrl:1
	v_add_f32_dpp v141, v141, v141 quad_perm:[1,0,3,2] row_mask:0xf bank_mask:0xf bound_ctrl:1
	v_pk_mul_f32 v[116:117], v[86:87], v[52:53]
	v_add_f32_dpp v140, v140, v140 quad_perm:[2,3,0,1] row_mask:0xf bank_mask:0xf bound_ctrl:1
	v_add_f32_dpp v141, v141, v141 quad_perm:[2,3,0,1] row_mask:0xf bank_mask:0xf bound_ctrl:1
	v_pk_mul_f32 v[118:119], v[88:89], v[46:47]
	v_add_f32_dpp v140, v140, v140 row_half_mirror row_mask:0xf bank_mask:0xf bound_ctrl:1
	v_add_f32_dpp v141, v141, v141 row_half_mirror row_mask:0xf bank_mask:0xf bound_ctrl:1
	v_pk_mul_f32 v[120:121], v[90:91], v[48:49]
	ds_read_b128 v[26:29], v100 offset:26112
	ds_read_b128 v[30:33], v100 offset:26128
	v_mul_f32_e32 v142, v140, v98
	v_mul_f32_e32 v143, v99, v0
	ds_read_b32 v94, v101 offset:26368
	v_add_f32_e32 v141, v142, v141
	ds_read_b64 v[96:97], v1 offset:26624
	v_add_f32_e32 v141, v143, v141
	v_pk_fma_f32 v[114:115], v[140:141], v[62:63], v[114:115] op_sel_hi:[0,1,1]
	v_pk_fma_f32 v[116:117], v[140:141], v[64:65], v[116:117] op_sel_hi:[0,1,1]
	v_cvt_pk_bf16_f32 v142, v141, v141
	v_pk_fma_f32 v[84:85], v[0:1], v[54:55], v[114:115] op_sel_hi:[0,1,1]
	global_store_short v159, v142, s[100:101]
	v_pk_fma_f32 v[118:119], v[140:141], v[58:59], v[118:119] op_sel_hi:[0,1,1]
	v_pk_fma_f32 v[86:87], v[0:1], v[56:57], v[116:117] op_sel_hi:[0,1,1]
	v_pk_fma_f32 v[120:121], v[140:141], v[60:61], v[120:121] op_sel_hi:[0,1,1]
	v_pk_fma_f32 v[88:89], v[0:1], v[42:43], v[118:119] op_sel_hi:[0,1,1]
	v_pk_fma_f32 v[90:91], v[0:1], v[44:45], v[120:121] op_sel_hi:[0,1,1]

.LBB0_869:
	v_readfirstlane_b32 s100, v92
	v_readfirstlane_b32 s101, v93
	s_sub_u32 s100, s100, m0
	s_subb_u32 s101, s101, 0
	s_waitcnt lgkmcnt(0)
	v_pk_fma_f32 v[106:107], v[84:85], v[34:35], 0 op_sel_hi:[1,1,0]
	v_pk_fma_f32 v[108:109], v[84:85], v[22:23], 0 op_sel_hi:[1,1,0]
	ds_read_b128 v[70:73], v100 offset:26656
	ds_read_b128 v[66:69], v100 offset:26672
	v_pk_fma_f32 v[106:107], v[86:87], v[36:37], v[106:107]
	v_pk_fma_f32 v[108:109], v[86:87], v[24:25], v[108:109]
	ds_read_b128 v[50:53], v100 offset:26912
	ds_read_b128 v[46:49], v100 offset:26928
	v_pk_fma_f32 v[106:107], v[88:89], v[38:39], v[106:107]
	v_pk_fma_f32 v[108:109], v[88:89], v[18:19], v[108:109]
	ds_read_b128 v[54:57], v100 offset:27168
	ds_read_b128 v[42:45], v100 offset:27184
	v_pk_fma_f32 v[106:107], v[90:91], v[40:41], v[106:107]
	v_pk_fma_f32 v[108:109], v[90:91], v[20:21], v[108:109]
	ds_read_b128 v[78:81], v100 offset:27424
	ds_read_b128 v[74:77], v100 offset:27440
	v_add_f32_e32 v130, v106, v107
	v_add_f32_e32 v131, v108, v109
	v_pk_mul_f32 v[114:115], v[84:85], v[2:3]
	v_add_f32_dpp v130, v130, v130 quad_perm:[1,0,3,2] row_mask:0xf bank_mask:0xf bound_ctrl:1
	v_add_f32_dpp v131, v131, v131 quad_perm:[1,0,3,2] row_mask:0xf bank_mask:0xf bound_ctrl:1
	v_pk_mul_f32 v[116:117], v[86:87], v[4:5]
	v_add_f32_dpp v130, v130, v130 quad_perm:[2,3,0,1] row_mask:0xf bank_mask:0xf bound_ctrl:1
	v_add_f32_dpp v131, v131, v131 quad_perm:[2,3,0,1] row_mask:0xf bank_mask:0xf bound_ctrl:1
	v_pk_mul_f32 v[118:119], v[88:89], v[6:7]
	v_add_f32_dpp v130, v130, v130 row_half_mirror row_mask:0xf bank_mask:0xf bound_ctrl:1
	v_add_f32_dpp v131, v131, v131 row_half_mirror row_mask:0xf bank_mask:0xf bound_ctrl:1
	v_pk_mul_f32 v[120:121], v[90:91], v[8:9]
	ds_read_b128 v[62:65], v100 offset:27680
	ds_read_b128 v[58:61], v100 offset:27696
	v_mul_f32_e32 v132, v130, v96
	v_mul_f32_e32 v133, v97, v94
	ds_read_b32 v0, v101 offset:27936
	v_add_f32_e32 v131, v132, v131
	ds_read_b64 v[98:99], v1 offset:28192
	v_add_f32_e32 v131, v133, v131
	v_pk_fma_f32 v[114:115], v[130:131], v[26:27], v[114:115] op_sel_hi:[0,1,1]
	v_pk_fma_f32 v[116:117], v[130:131], v[28:29], v[116:117] op_sel_hi:[0,1,1]
	v_cvt_pk_bf16_f32 v132, v131, v131
	v_pk_fma_f32 v[84:85], v[94:95], v[10:11], v[114:115] op_sel_hi:[0,1,1]
	global_store_short v144, v132, s[100:101]
	v_pk_fma_f32 v[118:119], v[130:131], v[30:31], v[118:119] op_sel_hi:[0,1,1]
	v_pk_fma_f32 v[86:87], v[94:95], v[12:13], v[116:117] op_sel_hi:[0,1,1]
	v_pk_fma_f32 v[120:121], v[130:131], v[32:33], v[120:121] op_sel_hi:[0,1,1]
	v_pk_fma_f32 v[88:89], v[94:95], v[14:15], v[118:119] op_sel_hi:[0,1,1]
	v_pk_fma_f32 v[90:91], v[94:95], v[16:17], v[120:121] op_sel_hi:[0,1,1]
	s_waitcnt lgkmcnt(0)
	v_pk_fma_f32 v[110:111], v[84:85], v[78:79], 0 op_sel_hi:[1,1,0]
	v_pk_fma_f32 v[112:113], v[84:85], v[70:71], 0 op_sel_hi:[1,1,0]
	ds_read_b128 v[22:25], v100 offset:28224
	ds_read_b128 v[18:21], v100 offset:28240
	v_pk_fma_f32 v[110:111], v[86:87], v[80:81], v[110:111]
	v_pk_fma_f32 v[112:113], v[86:87], v[72:73], v[112:113]
	ds_read_b128 v[2:5], v100 offset:28480
	ds_read_b128 v[6:9], v100 offset:28496
	v_pk_fma_f32 v[110:111], v[88:89], v[74:75], v[110:111]
	v_pk_fma_f32 v[112:113], v[88:89], v[66:67], v[112:113]
	ds_read_b128 v[10:13], v100 offset:28736
	ds_read_b128 v[14:17], v100 offset:28752
	v_pk_fma_f32 v[110:111], v[90:91], v[76:77], v[110:111]
	v_pk_fma_f32 v[112:113], v[90:91], v[68:69], v[112:113]
	ds_read_b128 v[34:37], v100 offset:28992
	ds_read_b128 v[38:41], v100 offset:29008
	v_add_f32_e32 v140, v110, v111
	v_add_f32_e32 v141, v112, v113
	v_pk_mul_f32 v[114:115], v[84:85], v[50:51]
	v_add_f32_dpp v140, v140, v140 quad_perm:[1,0,3,2] row_mask:0xf bank_mask:0xf bound_ctrl:1
	v_add_f32_dpp v141, v141, v141 quad_perm:[1,0,3,2] row_mask:0xf bank_mask:0xf bound_ctrl:1
	v_pk_mul_f32 v[116:117], v[86:87], v[52:53]
	v_add_f32_dpp v140, v140, v140 quad_perm:[2,3,0,1] row_mask:0xf bank_mask:0xf bound_ctrl:1
	v_add_f32_dpp v141, v141, v141 quad_perm:[2,3,0,1] row_mask:0xf bank_mask:0xf bound_ctrl:1
	v_pk_mul_f32 v[118:119], v[88:89], v[46:47]
	v_add_f32_dpp v140, v140, v140 row_half_mirror row_mask:0xf bank_mask:0xf bound_ctrl:1
	v_add_f32_dpp v141, v141, v141 row_half_mirror row_mask:0xf bank_mask:0xf bound_ctrl:1
	v_pk_mul_f32 v[120:121], v[90:91], v[48:49]
	ds_read_b128 v[26:29], v100 offset:29248
	ds_read_b128 v[30:33], v100 offset:29264
	v_mul_f32_e32 v142, v140, v98
	v_mul_f32_e32 v143, v99, v0
	ds_read_b32 v94, v101 offset:29504
	v_add_f32_e32 v141, v142, v141
	ds_read_b64 v[96:97], v1 offset:29760
	v_add_f32_e32 v141, v143, v141
	v_pk_fma_f32 v[114:115], v[140:141], v[62:63], v[114:115] op_sel_hi:[0,1,1]
	v_pk_fma_f32 v[116:117], v[140:141], v[64:65], v[116:117] op_sel_hi:[0,1,1]
	v_cvt_pk_bf16_f32 v142, v141, v141
	v_pk_fma_f32 v[84:85], v[0:1], v[54:55], v[114:115] op_sel_hi:[0,1,1]
	global_store_short v145, v142, s[100:101]
	v_pk_fma_f32 v[118:119], v[140:141], v[58:59], v[118:119] op_sel_hi:[0,1,1]
	v_pk_fma_f32 v[86:87], v[0:1], v[56:57], v[116:117] op_sel_hi:[0,1,1]
	v_pk_fma_f32 v[120:121], v[140:141], v[60:61], v[120:121] op_sel_hi:[0,1,1]
	v_pk_fma_f32 v[88:89], v[0:1], v[42:43], v[118:119] op_sel_hi:[0,1,1]
	v_pk_fma_f32 v[90:91], v[0:1], v[44:45], v[120:121] op_sel_hi:[0,1,1]
	s_waitcnt lgkmcnt(0)
	v_pk_fma_f32 v[106:107], v[84:85], v[34:35], 0 op_sel_hi:[1,1,0]
	v_pk_fma_f32 v[108:109], v[84:85], v[22:23], 0 op_sel_hi:[1,1,0]
	ds_read_b128 v[70:73], v100 offset:29792
	ds_read_b128 v[66:69], v100 offset:29808
	v_pk_fma_f32 v[106:107], v[86:87], v[36:37], v[106:107]
	v_pk_fma_f32 v[108:109], v[86:87], v[24:25], v[108:109]
	ds_read_b128 v[50:53], v100 offset:30048
	ds_read_b128 v[46:49], v100 offset:30064
	v_pk_fma_f32 v[106:107], v[88:89], v[38:39], v[106:107]
	v_pk_fma_f32 v[108:109], v[88:89], v[18:19], v[108:109]
	ds_read_b128 v[54:57], v100 offset:30304
	ds_read_b128 v[42:45], v100 offset:30320
	v_pk_fma_f32 v[106:107], v[90:91], v[40:41], v[106:107]
	v_pk_fma_f32 v[108:109], v[90:91], v[20:21], v[108:109]
	ds_read_b128 v[78:81], v100 offset:30560
	ds_read_b128 v[74:77], v100 offset:30576
	v_add_f32_e32 v130, v106, v107
	v_add_f32_e32 v131, v108, v109
	v_pk_mul_f32 v[114:115], v[84:85], v[2:3]
	v_add_f32_dpp v130, v130, v130 quad_perm:[1,0,3,2] row_mask:0xf bank_mask:0xf bound_ctrl:1
	v_add_f32_dpp v131, v131, v131 quad_perm:[1,0,3,2] row_mask:0xf bank_mask:0xf bound_ctrl:1
	v_pk_mul_f32 v[116:117], v[86:87], v[4:5]
	v_add_f32_dpp v130, v130, v130 quad_perm:[2,3,0,1] row_mask:0xf bank_mask:0xf bound_ctrl:1
	v_add_f32_dpp v131, v131, v131 quad_perm:[2,3,0,1] row_mask:0xf bank_mask:0xf bound_ctrl:1
	v_pk_mul_f32 v[118:119], v[88:89], v[6:7]
	v_add_f32_dpp v130, v130, v130 row_half_mirror row_mask:0xf bank_mask:0xf bound_ctrl:1
	v_add_f32_dpp v131, v131, v131 row_half_mirror row_mask:0xf bank_mask:0xf bound_ctrl:1
	v_pk_mul_f32 v[120:121], v[90:91], v[8:9]
	ds_read_b128 v[62:65], v100 offset:30816
	ds_read_b128 v[58:61], v100 offset:30832
	v_mul_f32_e32 v132, v130, v96
	v_mul_f32_e32 v133, v97, v94
	ds_read_b32 v0, v101 offset:31072
	v_add_f32_e32 v131, v132, v131
	ds_read_b64 v[98:99], v1 offset:31328
	v_add_f32_e32 v131, v133, v131
	v_pk_fma_f32 v[114:115], v[130:131], v[26:27], v[114:115] op_sel_hi:[0,1,1]
	v_pk_fma_f32 v[116:117], v[130:131], v[28:29], v[116:117] op_sel_hi:[0,1,1]
	v_cvt_pk_bf16_f32 v132, v131, v131
	v_pk_fma_f32 v[84:85], v[94:95], v[10:11], v[114:115] op_sel_hi:[0,1,1]
	global_store_short v146, v132, s[100:101]
	v_pk_fma_f32 v[118:119], v[130:131], v[30:31], v[118:119] op_sel_hi:[0,1,1]
	v_pk_fma_f32 v[86:87], v[94:95], v[12:13], v[116:117] op_sel_hi:[0,1,1]
	v_pk_fma_f32 v[120:121], v[130:131], v[32:33], v[120:121] op_sel_hi:[0,1,1]
	v_pk_fma_f32 v[88:89], v[94:95], v[14:15], v[118:119] op_sel_hi:[0,1,1]
	v_pk_fma_f32 v[90:91], v[94:95], v[16:17], v[120:121] op_sel_hi:[0,1,1]
	s_waitcnt lgkmcnt(0)
	v_pk_fma_f32 v[110:111], v[84:85], v[78:79], 0 op_sel_hi:[1,1,0]
	v_pk_fma_f32 v[112:113], v[84:85], v[70:71], 0 op_sel_hi:[1,1,0]
	ds_read_b128 v[22:25], v100 offset:31360
	ds_read_b128 v[18:21], v100 offset:31376
	v_pk_fma_f32 v[110:111], v[86:87], v[80:81], v[110:111]
	v_pk_fma_f32 v[112:113], v[86:87], v[72:73], v[112:113]
	ds_read_b128 v[2:5], v100 offset:31616
	ds_read_b128 v[6:9], v100 offset:31632
	v_pk_fma_f32 v[110:111], v[88:89], v[74:75], v[110:111]
	v_pk_fma_f32 v[112:113], v[88:89], v[66:67], v[112:113]
	ds_read_b128 v[10:13], v100 offset:31872
	ds_read_b128 v[14:17], v100 offset:31888
	v_pk_fma_f32 v[110:111], v[90:91], v[76:77], v[110:111]
	v_pk_fma_f32 v[112:113], v[90:91], v[68:69], v[112:113]
	ds_read_b128 v[34:37], v100 offset:32128
	ds_read_b128 v[38:41], v100 offset:32144
	v_add_f32_e32 v140, v110, v111
	v_add_f32_e32 v141, v112, v113
	v_pk_mul_f32 v[114:115], v[84:85], v[50:51]
	v_add_f32_dpp v140, v140, v140 quad_perm:[1,0,3,2] row_mask:0xf bank_mask:0xf bound_ctrl:1
	v_add_f32_dpp v141, v141, v141 quad_perm:[1,0,3,2] row_mask:0xf bank_mask:0xf bound_ctrl:1
	v_pk_mul_f32 v[116:117], v[86:87], v[52:53]
	v_add_f32_dpp v140, v140, v140 quad_perm:[2,3,0,1] row_mask:0xf bank_mask:0xf bound_ctrl:1
	v_add_f32_dpp v141, v141, v141 quad_perm:[2,3,0,1] row_mask:0xf bank_mask:0xf bound_ctrl:1
	v_pk_mul_f32 v[118:119], v[88:89], v[46:47]
	v_add_f32_dpp v140, v140, v140 row_half_mirror row_mask:0xf bank_mask:0xf bound_ctrl:1
	v_add_f32_dpp v141, v141, v141 row_half_mirror row_mask:0xf bank_mask:0xf bound_ctrl:1
	v_pk_mul_f32 v[120:121], v[90:91], v[48:49]
	ds_read_b128 v[26:29], v100 offset:32384
	ds_read_b128 v[30:33], v100 offset:32400
	v_mul_f32_e32 v142, v140, v98
	v_mul_f32_e32 v143, v99, v0
	ds_read_b32 v94, v101 offset:32640
	v_add_f32_e32 v141, v142, v141
	ds_read_b64 v[96:97], v1 offset:32896
	v_add_f32_e32 v141, v143, v141
	v_pk_fma_f32 v[114:115], v[140:141], v[62:63], v[114:115] op_sel_hi:[0,1,1]
	v_pk_fma_f32 v[116:117], v[140:141], v[64:65], v[116:117] op_sel_hi:[0,1,1]
	v_cvt_pk_bf16_f32 v142, v141, v141
	v_pk_fma_f32 v[84:85], v[0:1], v[54:55], v[114:115] op_sel_hi:[0,1,1]
	global_store_short v147, v142, s[100:101]
	v_pk_fma_f32 v[118:119], v[140:141], v[58:59], v[118:119] op_sel_hi:[0,1,1]
	v_pk_fma_f32 v[86:87], v[0:1], v[56:57], v[116:117] op_sel_hi:[0,1,1]
	v_pk_fma_f32 v[120:121], v[140:141], v[60:61], v[120:121] op_sel_hi:[0,1,1]
	v_pk_fma_f32 v[88:89], v[0:1], v[42:43], v[118:119] op_sel_hi:[0,1,1]
	v_pk_fma_f32 v[90:91], v[0:1], v[44:45], v[120:121] op_sel_hi:[0,1,1]
	s_waitcnt lgkmcnt(0)
	v_pk_fma_f32 v[106:107], v[84:85], v[34:35], 0 op_sel_hi:[1,1,0]
	v_pk_fma_f32 v[108:109], v[84:85], v[22:23], 0 op_sel_hi:[1,1,0]
	ds_read_b128 v[70:73], v100 offset:32928
	ds_read_b128 v[66:69], v100 offset:32944
	v_pk_fma_f32 v[106:107], v[86:87], v[36:37], v[106:107]
	v_pk_fma_f32 v[108:109], v[86:87], v[24:25], v[108:109]
	ds_read_b128 v[50:53], v100 offset:33184
	ds_read_b128 v[46:49], v100 offset:33200
	v_pk_fma_f32 v[106:107], v[88:89], v[38:39], v[106:107]
	v_pk_fma_f32 v[108:109], v[88:89], v[18:19], v[108:109]
	ds_read_b128 v[54:57], v100 offset:33440
	ds_read_b128 v[42:45], v100 offset:33456
	v_pk_fma_f32 v[106:107], v[90:91], v[40:41], v[106:107]
	v_pk_fma_f32 v[108:109], v[90:91], v[20:21], v[108:109]
	ds_read_b128 v[78:81], v100 offset:33696
	ds_read_b128 v[74:77], v100 offset:33712
	v_add_f32_e32 v130, v106, v107
	v_add_f32_e32 v131, v108, v109
	v_pk_mul_f32 v[114:115], v[84:85], v[2:3]
	v_add_f32_dpp v130, v130, v130 quad_perm:[1,0,3,2] row_mask:0xf bank_mask:0xf bound_ctrl:1
	v_add_f32_dpp v131, v131, v131 quad_perm:[1,0,3,2] row_mask:0xf bank_mask:0xf bound_ctrl:1
	v_pk_mul_f32 v[116:117], v[86:87], v[4:5]
	v_add_f32_dpp v130, v130, v130 quad_perm:[2,3,0,1] row_mask:0xf bank_mask:0xf bound_ctrl:1
	v_add_f32_dpp v131, v131, v131 quad_perm:[2,3,0,1] row_mask:0xf bank_mask:0xf bound_ctrl:1
	v_pk_mul_f32 v[118:119], v[88:89], v[6:7]
	v_add_f32_dpp v130, v130, v130 row_half_mirror row_mask:0xf bank_mask:0xf bound_ctrl:1
	v_add_f32_dpp v131, v131, v131 row_half_mirror row_mask:0xf bank_mask:0xf bound_ctrl:1
	v_pk_mul_f32 v[120:121], v[90:91], v[8:9]
	ds_read_b128 v[62:65], v100 offset:33952
	ds_read_b128 v[58:61], v100 offset:33968
	v_mul_f32_e32 v132, v130, v96
	v_mul_f32_e32 v133, v97, v94
	ds_read_b32 v0, v101 offset:34208
	v_add_f32_e32 v131, v132, v131
	ds_read_b64 v[98:99], v1 offset:34464
	v_add_f32_e32 v131, v133, v131
	v_pk_fma_f32 v[114:115], v[130:131], v[26:27], v[114:115] op_sel_hi:[0,1,1]
	v_pk_fma_f32 v[116:117], v[130:131], v[28:29], v[116:117] op_sel_hi:[0,1,1]
	v_cvt_pk_bf16_f32 v132, v131, v131
	v_pk_fma_f32 v[84:85], v[94:95], v[10:11], v[114:115] op_sel_hi:[0,1,1]
	global_store_short v148, v132, s[100:101]
	v_pk_fma_f32 v[118:119], v[130:131], v[30:31], v[118:119] op_sel_hi:[0,1,1]
	v_pk_fma_f32 v[86:87], v[94:95], v[12:13], v[116:117] op_sel_hi:[0,1,1]
	v_pk_fma_f32 v[120:121], v[130:131], v[32:33], v[120:121] op_sel_hi:[0,1,1]
	v_pk_fma_f32 v[88:89], v[94:95], v[14:15], v[118:119] op_sel_hi:[0,1,1]
	v_pk_fma_f32 v[90:91], v[94:95], v[16:17], v[120:121] op_sel_hi:[0,1,1]
	s_waitcnt lgkmcnt(0)
	v_pk_fma_f32 v[110:111], v[84:85], v[78:79], 0 op_sel_hi:[1,1,0]
	v_pk_fma_f32 v[112:113], v[84:85], v[70:71], 0 op_sel_hi:[1,1,0]
	ds_read_b128 v[22:25], v100 offset:34496
	ds_read_b128 v[18:21], v100 offset:34512
	v_pk_fma_f32 v[110:111], v[86:87], v[80:81], v[110:111]
	v_pk_fma_f32 v[112:113], v[86:87], v[72:73], v[112:113]
	ds_read_b128 v[2:5], v100 offset:34752
	ds_read_b128 v[6:9], v100 offset:34768
	v_pk_fma_f32 v[110:111], v[88:89], v[74:75], v[110:111]
	v_pk_fma_f32 v[112:113], v[88:89], v[66:67], v[112:113]
	ds_read_b128 v[10:13], v100 offset:35008
	ds_read_b128 v[14:17], v100 offset:35024
	v_pk_fma_f32 v[110:111], v[90:91], v[76:77], v[110:111]
	v_pk_fma_f32 v[112:113], v[90:91], v[68:69], v[112:113]
	ds_read_b128 v[34:37], v100 offset:35264
	ds_read_b128 v[38:41], v100 offset:35280
	v_add_f32_e32 v140, v110, v111
	v_add_f32_e32 v141, v112, v113
	v_pk_mul_f32 v[114:115], v[84:85], v[50:51]
	v_add_f32_dpp v140, v140, v140 quad_perm:[1,0,3,2] row_mask:0xf bank_mask:0xf bound_ctrl:1
	v_add_f32_dpp v141, v141, v141 quad_perm:[1,0,3,2] row_mask:0xf bank_mask:0xf bound_ctrl:1
	v_pk_mul_f32 v[116:117], v[86:87], v[52:53]
	v_add_f32_dpp v140, v140, v140 quad_perm:[2,3,0,1] row_mask:0xf bank_mask:0xf bound_ctrl:1
	v_add_f32_dpp v141, v141, v141 quad_perm:[2,3,0,1] row_mask:0xf bank_mask:0xf bound_ctrl:1
	v_pk_mul_f32 v[118:119], v[88:89], v[46:47]
	v_add_f32_dpp v140, v140, v140 row_half_mirror row_mask:0xf bank_mask:0xf bound_ctrl:1
	v_add_f32_dpp v141, v141, v141 row_half_mirror row_mask:0xf bank_mask:0xf bound_ctrl:1
	v_pk_mul_f32 v[120:121], v[90:91], v[48:49]
	ds_read_b128 v[26:29], v100 offset:35520
	ds_read_b128 v[30:33], v100 offset:35536
	v_mul_f32_e32 v142, v140, v98
	v_mul_f32_e32 v143, v99, v0
	ds_read_b32 v94, v101 offset:35776
	v_add_f32_e32 v141, v142, v141
	ds_read_b64 v[96:97], v1 offset:36032
	v_add_f32_e32 v141, v143, v141
	v_pk_fma_f32 v[114:115], v[140:141], v[62:63], v[114:115] op_sel_hi:[0,1,1]
	v_pk_fma_f32 v[116:117], v[140:141], v[64:65], v[116:117] op_sel_hi:[0,1,1]
	v_cvt_pk_bf16_f32 v142, v141, v141
	v_pk_fma_f32 v[84:85], v[0:1], v[54:55], v[114:115] op_sel_hi:[0,1,1]
	global_store_short v149, v142, s[100:101]
	v_pk_fma_f32 v[118:119], v[140:141], v[58:59], v[118:119] op_sel_hi:[0,1,1]
	v_pk_fma_f32 v[86:87], v[0:1], v[56:57], v[116:117] op_sel_hi:[0,1,1]
	v_pk_fma_f32 v[120:121], v[140:141], v[60:61], v[120:121] op_sel_hi:[0,1,1]
	v_pk_fma_f32 v[88:89], v[0:1], v[42:43], v[118:119] op_sel_hi:[0,1,1]
	v_pk_fma_f32 v[90:91], v[0:1], v[44:45], v[120:121] op_sel_hi:[0,1,1]
	s_waitcnt lgkmcnt(0)
	v_pk_fma_f32 v[106:107], v[84:85], v[34:35], 0 op_sel_hi:[1,1,0]
	v_pk_fma_f32 v[108:109], v[84:85], v[22:23], 0 op_sel_hi:[1,1,0]
	ds_read_b128 v[70:73], v100 offset:36064
	ds_read_b128 v[66:69], v100 offset:36080
	v_pk_fma_f32 v[106:107], v[86:87], v[36:37], v[106:107]
	v_pk_fma_f32 v[108:109], v[86:87], v[24:25], v[108:109]
	ds_read_b128 v[50:53], v100 offset:36320
	ds_read_b128 v[46:49], v100 offset:36336
	v_pk_fma_f32 v[106:107], v[88:89], v[38:39], v[106:107]
	v_pk_fma_f32 v[108:109], v[88:89], v[18:19], v[108:109]
	ds_read_b128 v[54:57], v100 offset:36576
	ds_read_b128 v[42:45], v100 offset:36592
	v_pk_fma_f32 v[106:107], v[90:91], v[40:41], v[106:107]
	v_pk_fma_f32 v[108:109], v[90:91], v[20:21], v[108:109]
	ds_read_b128 v[78:81], v100 offset:36832
	ds_read_b128 v[74:77], v100 offset:36848
	v_add_f32_e32 v130, v106, v107
	v_add_f32_e32 v131, v108, v109
	v_pk_mul_f32 v[114:115], v[84:85], v[2:3]
	v_add_f32_dpp v130, v130, v130 quad_perm:[1,0,3,2] row_mask:0xf bank_mask:0xf bound_ctrl:1
	v_add_f32_dpp v131, v131, v131 quad_perm:[1,0,3,2] row_mask:0xf bank_mask:0xf bound_ctrl:1
	v_pk_mul_f32 v[116:117], v[86:87], v[4:5]
	v_add_f32_dpp v130, v130, v130 quad_perm:[2,3,0,1] row_mask:0xf bank_mask:0xf bound_ctrl:1
	v_add_f32_dpp v131, v131, v131 quad_perm:[2,3,0,1] row_mask:0xf bank_mask:0xf bound_ctrl:1
	v_pk_mul_f32 v[118:119], v[88:89], v[6:7]
	v_add_f32_dpp v130, v130, v130 row_half_mirror row_mask:0xf bank_mask:0xf bound_ctrl:1
	v_add_f32_dpp v131, v131, v131 row_half_mirror row_mask:0xf bank_mask:0xf bound_ctrl:1
	v_pk_mul_f32 v[120:121], v[90:91], v[8:9]
	ds_read_b128 v[62:65], v100 offset:37088
	ds_read_b128 v[58:61], v100 offset:37104
	v_mul_f32_e32 v132, v130, v96
	v_mul_f32_e32 v133, v97, v94
	ds_read_b32 v0, v101 offset:37344
	v_add_f32_e32 v131, v132, v131
	ds_read_b64 v[98:99], v1 offset:37600
	v_add_f32_e32 v131, v133, v131
	v_pk_fma_f32 v[114:115], v[130:131], v[26:27], v[114:115] op_sel_hi:[0,1,1]
	v_pk_fma_f32 v[116:117], v[130:131], v[28:29], v[116:117] op_sel_hi:[0,1,1]
	v_cvt_pk_bf16_f32 v132, v131, v131
	v_pk_fma_f32 v[84:85], v[94:95], v[10:11], v[114:115] op_sel_hi:[0,1,1]
	global_store_short v150, v132, s[100:101]
	v_pk_fma_f32 v[118:119], v[130:131], v[30:31], v[118:119] op_sel_hi:[0,1,1]
	v_pk_fma_f32 v[86:87], v[94:95], v[12:13], v[116:117] op_sel_hi:[0,1,1]
	v_pk_fma_f32 v[120:121], v[130:131], v[32:33], v[120:121] op_sel_hi:[0,1,1]
	v_pk_fma_f32 v[88:89], v[94:95], v[14:15], v[118:119] op_sel_hi:[0,1,1]
	v_pk_fma_f32 v[90:91], v[94:95], v[16:17], v[120:121] op_sel_hi:[0,1,1]
	s_waitcnt lgkmcnt(0)
	v_pk_fma_f32 v[110:111], v[84:85], v[78:79], 0 op_sel_hi:[1,1,0]
	v_pk_fma_f32 v[112:113], v[84:85], v[70:71], 0 op_sel_hi:[1,1,0]
	ds_read_b128 v[22:25], v100 offset:37632
	ds_read_b128 v[18:21], v100 offset:37648
	v_pk_fma_f32 v[110:111], v[86:87], v[80:81], v[110:111]
	v_pk_fma_f32 v[112:113], v[86:87], v[72:73], v[112:113]
	ds_read_b128 v[2:5], v100 offset:37888
	ds_read_b128 v[6:9], v100 offset:37904
	v_pk_fma_f32 v[110:111], v[88:89], v[74:75], v[110:111]
	v_pk_fma_f32 v[112:113], v[88:89], v[66:67], v[112:113]
	ds_read_b128 v[10:13], v100 offset:38144
	ds_read_b128 v[14:17], v100 offset:38160
	v_pk_fma_f32 v[110:111], v[90:91], v[76:77], v[110:111]
	v_pk_fma_f32 v[112:113], v[90:91], v[68:69], v[112:113]
	ds_read_b128 v[34:37], v100 offset:38400
	ds_read_b128 v[38:41], v100 offset:38416
	v_add_f32_e32 v140, v110, v111
	v_add_f32_e32 v141, v112, v113
	v_pk_mul_f32 v[114:115], v[84:85], v[50:51]
	v_add_f32_dpp v140, v140, v140 quad_perm:[1,0,3,2] row_mask:0xf bank_mask:0xf bound_ctrl:1
	v_add_f32_dpp v141, v141, v141 quad_perm:[1,0,3,2] row_mask:0xf bank_mask:0xf bound_ctrl:1
	v_pk_mul_f32 v[116:117], v[86:87], v[52:53]
	v_add_f32_dpp v140, v140, v140 quad_perm:[2,3,0,1] row_mask:0xf bank_mask:0xf bound_ctrl:1
	v_add_f32_dpp v141, v141, v141 quad_perm:[2,3,0,1] row_mask:0xf bank_mask:0xf bound_ctrl:1
	v_pk_mul_f32 v[118:119], v[88:89], v[46:47]
	v_add_f32_dpp v140, v140, v140 row_half_mirror row_mask:0xf bank_mask:0xf bound_ctrl:1
	v_add_f32_dpp v141, v141, v141 row_half_mirror row_mask:0xf bank_mask:0xf bound_ctrl:1
	v_pk_mul_f32 v[120:121], v[90:91], v[48:49]
	ds_read_b128 v[26:29], v100 offset:38656
	ds_read_b128 v[30:33], v100 offset:38672
	v_mul_f32_e32 v142, v140, v98
	v_mul_f32_e32 v143, v99, v0
	ds_read_b32 v94, v101 offset:38912
	v_add_f32_e32 v141, v142, v141
	ds_read_b64 v[96:97], v1 offset:39168
	v_add_f32_e32 v141, v143, v141
	v_pk_fma_f32 v[114:115], v[140:141], v[62:63], v[114:115] op_sel_hi:[0,1,1]
	v_pk_fma_f32 v[116:117], v[140:141], v[64:65], v[116:117] op_sel_hi:[0,1,1]
	v_cvt_pk_bf16_f32 v142, v141, v141
	v_pk_fma_f32 v[84:85], v[0:1], v[54:55], v[114:115] op_sel_hi:[0,1,1]
	global_store_short v151, v142, s[100:101]
	v_pk_fma_f32 v[118:119], v[140:141], v[58:59], v[118:119] op_sel_hi:[0,1,1]
	v_pk_fma_f32 v[86:87], v[0:1], v[56:57], v[116:117] op_sel_hi:[0,1,1]
	v_pk_fma_f32 v[120:121], v[140:141], v[60:61], v[120:121] op_sel_hi:[0,1,1]
	v_pk_fma_f32 v[88:89], v[0:1], v[42:43], v[118:119] op_sel_hi:[0,1,1]
	v_pk_fma_f32 v[90:91], v[0:1], v[44:45], v[120:121] op_sel_hi:[0,1,1]
	s_waitcnt lgkmcnt(0)
	v_pk_fma_f32 v[106:107], v[84:85], v[34:35], 0 op_sel_hi:[1,1,0]
	v_pk_fma_f32 v[108:109], v[84:85], v[22:23], 0 op_sel_hi:[1,1,0]
	ds_read_b128 v[70:73], v100 offset:39200
	ds_read_b128 v[66:69], v100 offset:39216
	v_pk_fma_f32 v[106:107], v[86:87], v[36:37], v[106:107]
	v_pk_fma_f32 v[108:109], v[86:87], v[24:25], v[108:109]
	ds_read_b128 v[50:53], v100 offset:39456
	ds_read_b128 v[46:49], v100 offset:39472
	v_pk_fma_f32 v[106:107], v[88:89], v[38:39], v[106:107]
	v_pk_fma_f32 v[108:109], v[88:89], v[18:19], v[108:109]
	ds_read_b128 v[54:57], v100 offset:39712
	ds_read_b128 v[42:45], v100 offset:39728
	v_pk_fma_f32 v[106:107], v[90:91], v[40:41], v[106:107]
	v_pk_fma_f32 v[108:109], v[90:91], v[20:21], v[108:109]
	ds_read_b128 v[78:81], v100 offset:39968
	ds_read_b128 v[74:77], v100 offset:39984
	v_add_f32_e32 v130, v106, v107
	v_add_f32_e32 v131, v108, v109
	v_pk_mul_f32 v[114:115], v[84:85], v[2:3]
	v_add_f32_dpp v130, v130, v130 quad_perm:[1,0,3,2] row_mask:0xf bank_mask:0xf bound_ctrl:1
	v_add_f32_dpp v131, v131, v131 quad_perm:[1,0,3,2] row_mask:0xf bank_mask:0xf bound_ctrl:1
	v_pk_mul_f32 v[116:117], v[86:87], v[4:5]
	v_add_f32_dpp v130, v130, v130 quad_perm:[2,3,0,1] row_mask:0xf bank_mask:0xf bound_ctrl:1
	v_add_f32_dpp v131, v131, v131 quad_perm:[2,3,0,1] row_mask:0xf bank_mask:0xf bound_ctrl:1
	v_pk_mul_f32 v[118:119], v[88:89], v[6:7]
	v_add_f32_dpp v130, v130, v130 row_half_mirror row_mask:0xf bank_mask:0xf bound_ctrl:1
	v_add_f32_dpp v131, v131, v131 row_half_mirror row_mask:0xf bank_mask:0xf bound_ctrl:1
	v_pk_mul_f32 v[120:121], v[90:91], v[8:9]
	ds_read_b128 v[62:65], v100 offset:40224
	ds_read_b128 v[58:61], v100 offset:40240
	v_mul_f32_e32 v132, v130, v96
	v_mul_f32_e32 v133, v97, v94
	ds_read_b32 v0, v101 offset:40480
	v_add_f32_e32 v131, v132, v131
	ds_read_b64 v[98:99], v1 offset:40736
	v_add_f32_e32 v131, v133, v131
	v_pk_fma_f32 v[114:115], v[130:131], v[26:27], v[114:115] op_sel_hi:[0,1,1]
	v_pk_fma_f32 v[116:117], v[130:131], v[28:29], v[116:117] op_sel_hi:[0,1,1]
	v_cvt_pk_bf16_f32 v132, v131, v131
	v_pk_fma_f32 v[84:85], v[94:95], v[10:11], v[114:115] op_sel_hi:[0,1,1]
	global_store_short v152, v132, s[100:101]
	v_pk_fma_f32 v[118:119], v[130:131], v[30:31], v[118:119] op_sel_hi:[0,1,1]
	v_pk_fma_f32 v[86:87], v[94:95], v[12:13], v[116:117] op_sel_hi:[0,1,1]
	v_pk_fma_f32 v[120:121], v[130:131], v[32:33], v[120:121] op_sel_hi:[0,1,1]
	v_pk_fma_f32 v[88:89], v[94:95], v[14:15], v[118:119] op_sel_hi:[0,1,1]
	v_pk_fma_f32 v[90:91], v[94:95], v[16:17], v[120:121] op_sel_hi:[0,1,1]
	s_waitcnt lgkmcnt(0)
	v_pk_fma_f32 v[110:111], v[84:85], v[78:79], 0 op_sel_hi:[1,1,0]
	v_pk_fma_f32 v[112:113], v[84:85], v[70:71], 0 op_sel_hi:[1,1,0]
	ds_read_b128 v[22:25], v100 offset:40768
	ds_read_b128 v[18:21], v100 offset:40784
	v_pk_fma_f32 v[110:111], v[86:87], v[80:81], v[110:111]
	v_pk_fma_f32 v[112:113], v[86:87], v[72:73], v[112:113]
	ds_read_b128 v[2:5], v100 offset:41024
	ds_read_b128 v[6:9], v100 offset:41040
	v_pk_fma_f32 v[110:111], v[88:89], v[74:75], v[110:111]
	v_pk_fma_f32 v[112:113], v[88:89], v[66:67], v[112:113]
	ds_read_b128 v[10:13], v100 offset:41280
	ds_read_b128 v[14:17], v100 offset:41296
	v_pk_fma_f32 v[110:111], v[90:91], v[76:77], v[110:111]
	v_pk_fma_f32 v[112:113], v[90:91], v[68:69], v[112:113]
	ds_read_b128 v[34:37], v100 offset:41536
	ds_read_b128 v[38:41], v100 offset:41552
	v_add_f32_e32 v140, v110, v111
	v_add_f32_e32 v141, v112, v113
	v_pk_mul_f32 v[114:115], v[84:85], v[50:51]
	v_add_f32_dpp v140, v140, v140 quad_perm:[1,0,3,2] row_mask:0xf bank_mask:0xf bound_ctrl:1
	v_add_f32_dpp v141, v141, v141 quad_perm:[1,0,3,2] row_mask:0xf bank_mask:0xf bound_ctrl:1
	v_pk_mul_f32 v[116:117], v[86:87], v[52:53]
	v_add_f32_dpp v140, v140, v140 quad_perm:[2,3,0,1] row_mask:0xf bank_mask:0xf bound_ctrl:1
	v_add_f32_dpp v141, v141, v141 quad_perm:[2,3,0,1] row_mask:0xf bank_mask:0xf bound_ctrl:1
	v_pk_mul_f32 v[118:119], v[88:89], v[46:47]
	v_add_f32_dpp v140, v140, v140 row_half_mirror row_mask:0xf bank_mask:0xf bound_ctrl:1
	v_add_f32_dpp v141, v141, v141 row_half_mirror row_mask:0xf bank_mask:0xf bound_ctrl:1
	v_pk_mul_f32 v[120:121], v[90:91], v[48:49]
	ds_read_b128 v[26:29], v100 offset:41792
	ds_read_b128 v[30:33], v100 offset:41808
	v_mul_f32_e32 v142, v140, v98
	v_mul_f32_e32 v143, v99, v0
	ds_read_b32 v94, v101 offset:42048
	v_add_f32_e32 v141, v142, v141
	ds_read_b64 v[96:97], v1 offset:42304
	v_add_f32_e32 v141, v143, v141
	v_pk_fma_f32 v[114:115], v[140:141], v[62:63], v[114:115] op_sel_hi:[0,1,1]
	v_pk_fma_f32 v[116:117], v[140:141], v[64:65], v[116:117] op_sel_hi:[0,1,1]
	v_cvt_pk_bf16_f32 v142, v141, v141
	v_pk_fma_f32 v[84:85], v[0:1], v[54:55], v[114:115] op_sel_hi:[0,1,1]
	global_store_short v153, v142, s[100:101]
	v_pk_fma_f32 v[118:119], v[140:141], v[58:59], v[118:119] op_sel_hi:[0,1,1]
	v_pk_fma_f32 v[86:87], v[0:1], v[56:57], v[116:117] op_sel_hi:[0,1,1]
	v_pk_fma_f32 v[120:121], v[140:141], v[60:61], v[120:121] op_sel_hi:[0,1,1]
	v_pk_fma_f32 v[88:89], v[0:1], v[42:43], v[118:119] op_sel_hi:[0,1,1]
	v_pk_fma_f32 v[90:91], v[0:1], v[44:45], v[120:121] op_sel_hi:[0,1,1]
	s_waitcnt lgkmcnt(0)
	v_pk_fma_f32 v[106:107], v[84:85], v[34:35], 0 op_sel_hi:[1,1,0]
	v_pk_fma_f32 v[108:109], v[84:85], v[22:23], 0 op_sel_hi:[1,1,0]
	ds_read_b128 v[70:73], v100 offset:42336
	ds_read_b128 v[66:69], v100 offset:42352
	v_pk_fma_f32 v[106:107], v[86:87], v[36:37], v[106:107]
	v_pk_fma_f32 v[108:109], v[86:87], v[24:25], v[108:109]
	ds_read_b128 v[50:53], v100 offset:42592
	ds_read_b128 v[46:49], v100 offset:42608
	v_pk_fma_f32 v[106:107], v[88:89], v[38:39], v[106:107]
	v_pk_fma_f32 v[108:109], v[88:89], v[18:19], v[108:109]
	ds_read_b128 v[54:57], v100 offset:42848
	ds_read_b128 v[42:45], v100 offset:42864
	v_pk_fma_f32 v[106:107], v[90:91], v[40:41], v[106:107]
	v_pk_fma_f32 v[108:109], v[90:91], v[20:21], v[108:109]
	ds_read_b128 v[78:81], v100 offset:43104
	ds_read_b128 v[74:77], v100 offset:43120
	v_add_f32_e32 v130, v106, v107
	v_add_f32_e32 v131, v108, v109
	v_pk_mul_f32 v[114:115], v[84:85], v[2:3]
	v_add_f32_dpp v130, v130, v130 quad_perm:[1,0,3,2] row_mask:0xf bank_mask:0xf bound_ctrl:1
	v_add_f32_dpp v131, v131, v131 quad_perm:[1,0,3,2] row_mask:0xf bank_mask:0xf bound_ctrl:1
	v_pk_mul_f32 v[116:117], v[86:87], v[4:5]
	v_add_f32_dpp v130, v130, v130 quad_perm:[2,3,0,1] row_mask:0xf bank_mask:0xf bound_ctrl:1
	v_add_f32_dpp v131, v131, v131 quad_perm:[2,3,0,1] row_mask:0xf bank_mask:0xf bound_ctrl:1
	v_pk_mul_f32 v[118:119], v[88:89], v[6:7]
	v_add_f32_dpp v130, v130, v130 row_half_mirror row_mask:0xf bank_mask:0xf bound_ctrl:1
	v_add_f32_dpp v131, v131, v131 row_half_mirror row_mask:0xf bank_mask:0xf bound_ctrl:1
	v_pk_mul_f32 v[120:121], v[90:91], v[8:9]
	ds_read_b128 v[62:65], v100 offset:43360
	ds_read_b128 v[58:61], v100 offset:43376
	v_mul_f32_e32 v132, v130, v96
	v_mul_f32_e32 v133, v97, v94
	ds_read_b32 v0, v101 offset:43616
	v_add_f32_e32 v131, v132, v131
	ds_read_b64 v[98:99], v1 offset:43872
	v_add_f32_e32 v131, v133, v131
	v_pk_fma_f32 v[114:115], v[130:131], v[26:27], v[114:115] op_sel_hi:[0,1,1]
	v_pk_fma_f32 v[116:117], v[130:131], v[28:29], v[116:117] op_sel_hi:[0,1,1]
	v_cvt_pk_bf16_f32 v132, v131, v131
	v_pk_fma_f32 v[84:85], v[94:95], v[10:11], v[114:115] op_sel_hi:[0,1,1]
	global_store_short v154, v132, s[100:101]
	v_pk_fma_f32 v[118:119], v[130:131], v[30:31], v[118:119] op_sel_hi:[0,1,1]
	v_pk_fma_f32 v[86:87], v[94:95], v[12:13], v[116:117] op_sel_hi:[0,1,1]
	v_pk_fma_f32 v[120:121], v[130:131], v[32:33], v[120:121] op_sel_hi:[0,1,1]
	v_pk_fma_f32 v[88:89], v[94:95], v[14:15], v[118:119] op_sel_hi:[0,1,1]
	v_pk_fma_f32 v[90:91], v[94:95], v[16:17], v[120:121] op_sel_hi:[0,1,1]
	s_waitcnt lgkmcnt(0)
	v_pk_fma_f32 v[110:111], v[84:85], v[78:79], 0 op_sel_hi:[1,1,0]
	v_pk_fma_f32 v[112:113], v[84:85], v[70:71], 0 op_sel_hi:[1,1,0]
	ds_read_b128 v[22:25], v100 offset:43904
	ds_read_b128 v[18:21], v100 offset:43920
	v_pk_fma_f32 v[110:111], v[86:87], v[80:81], v[110:111]
	v_pk_fma_f32 v[112:113], v[86:87], v[72:73], v[112:113]
	ds_read_b128 v[2:5], v100 offset:44160
	ds_read_b128 v[6:9], v100 offset:44176
	v_pk_fma_f32 v[110:111], v[88:89], v[74:75], v[110:111]
	v_pk_fma_f32 v[112:113], v[88:89], v[66:67], v[112:113]
	ds_read_b128 v[10:13], v100 offset:44416
	ds_read_b128 v[14:17], v100 offset:44432
	v_pk_fma_f32 v[110:111], v[90:91], v[76:77], v[110:111]
	v_pk_fma_f32 v[112:113], v[90:91], v[68:69], v[112:113]
	ds_read_b128 v[34:37], v100 offset:44672
	ds_read_b128 v[38:41], v100 offset:44688
	v_add_f32_e32 v140, v110, v111
	v_add_f32_e32 v141, v112, v113
	v_pk_mul_f32 v[114:115], v[84:85], v[50:51]
	v_add_f32_dpp v140, v140, v140 quad_perm:[1,0,3,2] row_mask:0xf bank_mask:0xf bound_ctrl:1
	v_add_f32_dpp v141, v141, v141 quad_perm:[1,0,3,2] row_mask:0xf bank_mask:0xf bound_ctrl:1
	v_pk_mul_f32 v[116:117], v[86:87], v[52:53]
	v_add_f32_dpp v140, v140, v140 quad_perm:[2,3,0,1] row_mask:0xf bank_mask:0xf bound_ctrl:1
	v_add_f32_dpp v141, v141, v141 quad_perm:[2,3,0,1] row_mask:0xf bank_mask:0xf bound_ctrl:1
	v_pk_mul_f32 v[118:119], v[88:89], v[46:47]
	v_add_f32_dpp v140, v140, v140 row_half_mirror row_mask:0xf bank_mask:0xf bound_ctrl:1
	v_add_f32_dpp v141, v141, v141 row_half_mirror row_mask:0xf bank_mask:0xf bound_ctrl:1
	v_pk_mul_f32 v[120:121], v[90:91], v[48:49]
	ds_read_b128 v[26:29], v100 offset:44928
	ds_read_b128 v[30:33], v100 offset:44944
	v_mul_f32_e32 v142, v140, v98
	v_mul_f32_e32 v143, v99, v0
	ds_read_b32 v94, v101 offset:45184
	v_add_f32_e32 v141, v142, v141
	ds_read_b64 v[96:97], v1 offset:45440
	v_add_f32_e32 v141, v143, v141
	v_pk_fma_f32 v[114:115], v[140:141], v[62:63], v[114:115] op_sel_hi:[0,1,1]
	v_pk_fma_f32 v[116:117], v[140:141], v[64:65], v[116:117] op_sel_hi:[0,1,1]
	v_cvt_pk_bf16_f32 v142, v141, v141
	v_pk_fma_f32 v[84:85], v[0:1], v[54:55], v[114:115] op_sel_hi:[0,1,1]
	global_store_short v155, v142, s[100:101]
	v_pk_fma_f32 v[118:119], v[140:141], v[58:59], v[118:119] op_sel_hi:[0,1,1]
	v_pk_fma_f32 v[86:87], v[0:1], v[56:57], v[116:117] op_sel_hi:[0,1,1]
	v_pk_fma_f32 v[120:121], v[140:141], v[60:61], v[120:121] op_sel_hi:[0,1,1]
	v_pk_fma_f32 v[88:89], v[0:1], v[42:43], v[118:119] op_sel_hi:[0,1,1]
	v_pk_fma_f32 v[90:91], v[0:1], v[44:45], v[120:121] op_sel_hi:[0,1,1]
	s_waitcnt lgkmcnt(0)
	v_pk_fma_f32 v[106:107], v[84:85], v[34:35], 0 op_sel_hi:[1,1,0]
	v_pk_fma_f32 v[108:109], v[84:85], v[22:23], 0 op_sel_hi:[1,1,0]
	ds_read_b128 v[70:73], v100 offset:45472
	ds_read_b128 v[66:69], v100 offset:45488
	v_pk_fma_f32 v[106:107], v[86:87], v[36:37], v[106:107]
	v_pk_fma_f32 v[108:109], v[86:87], v[24:25], v[108:109]
	ds_read_b128 v[50:53], v100 offset:45728
	ds_read_b128 v[46:49], v100 offset:45744
	v_pk_fma_f32 v[106:107], v[88:89], v[38:39], v[106:107]
	v_pk_fma_f32 v[108:109], v[88:89], v[18:19], v[108:109]
	ds_read_b128 v[54:57], v100 offset:45984
	ds_read_b128 v[42:45], v100 offset:46000
	v_pk_fma_f32 v[106:107], v[90:91], v[40:41], v[106:107]
	v_pk_fma_f32 v[108:109], v[90:91], v[20:21], v[108:109]
	ds_read_b128 v[78:81], v100 offset:46240
	ds_read_b128 v[74:77], v100 offset:46256
	v_add_f32_e32 v130, v106, v107
	v_add_f32_e32 v131, v108, v109
	v_pk_mul_f32 v[114:115], v[84:85], v[2:3]
	v_add_f32_dpp v130, v130, v130 quad_perm:[1,0,3,2] row_mask:0xf bank_mask:0xf bound_ctrl:1
	v_add_f32_dpp v131, v131, v131 quad_perm:[1,0,3,2] row_mask:0xf bank_mask:0xf bound_ctrl:1
	v_pk_mul_f32 v[116:117], v[86:87], v[4:5]
	v_add_f32_dpp v130, v130, v130 quad_perm:[2,3,0,1] row_mask:0xf bank_mask:0xf bound_ctrl:1
	v_add_f32_dpp v131, v131, v131 quad_perm:[2,3,0,1] row_mask:0xf bank_mask:0xf bound_ctrl:1
	v_pk_mul_f32 v[118:119], v[88:89], v[6:7]
	v_add_f32_dpp v130, v130, v130 row_half_mirror row_mask:0xf bank_mask:0xf bound_ctrl:1
	v_add_f32_dpp v131, v131, v131 row_half_mirror row_mask:0xf bank_mask:0xf bound_ctrl:1
	v_pk_mul_f32 v[120:121], v[90:91], v[8:9]
	ds_read_b128 v[62:65], v100 offset:46496
	ds_read_b128 v[58:61], v100 offset:46512
	v_mul_f32_e32 v132, v130, v96
	v_mul_f32_e32 v133, v97, v94
	ds_read_b32 v0, v101 offset:46752
	v_add_f32_e32 v131, v132, v131
	ds_read_b64 v[98:99], v1 offset:47008
	v_add_f32_e32 v131, v133, v131
	v_pk_fma_f32 v[114:115], v[130:131], v[26:27], v[114:115] op_sel_hi:[0,1,1]
	v_pk_fma_f32 v[116:117], v[130:131], v[28:29], v[116:117] op_sel_hi:[0,1,1]
	v_cvt_pk_bf16_f32 v132, v131, v131
	v_pk_fma_f32 v[84:85], v[94:95], v[10:11], v[114:115] op_sel_hi:[0,1,1]
	global_store_short v156, v132, s[100:101]
	v_pk_fma_f32 v[118:119], v[130:131], v[30:31], v[118:119] op_sel_hi:[0,1,1]
	v_pk_fma_f32 v[86:87], v[94:95], v[12:13], v[116:117] op_sel_hi:[0,1,1]
	v_pk_fma_f32 v[120:121], v[130:131], v[32:33], v[120:121] op_sel_hi:[0,1,1]
	v_pk_fma_f32 v[88:89], v[94:95], v[14:15], v[118:119] op_sel_hi:[0,1,1]
	v_pk_fma_f32 v[90:91], v[94:95], v[16:17], v[120:121] op_sel_hi:[0,1,1]
	s_waitcnt lgkmcnt(0)
	v_pk_fma_f32 v[110:111], v[84:85], v[78:79], 0 op_sel_hi:[1,1,0]
	v_pk_fma_f32 v[112:113], v[84:85], v[70:71], 0 op_sel_hi:[1,1,0]
	ds_read_b128 v[22:25], v100 offset:47040
	ds_read_b128 v[18:21], v100 offset:47056
	v_pk_fma_f32 v[110:111], v[86:87], v[80:81], v[110:111]
	v_pk_fma_f32 v[112:113], v[86:87], v[72:73], v[112:113]
	ds_read_b128 v[2:5], v100 offset:47296
	ds_read_b128 v[6:9], v100 offset:47312
	v_pk_fma_f32 v[110:111], v[88:89], v[74:75], v[110:111]
	v_pk_fma_f32 v[112:113], v[88:89], v[66:67], v[112:113]
	ds_read_b128 v[10:13], v100 offset:47552
	ds_read_b128 v[14:17], v100 offset:47568
	v_pk_fma_f32 v[110:111], v[90:91], v[76:77], v[110:111]
	v_pk_fma_f32 v[112:113], v[90:91], v[68:69], v[112:113]
	ds_read_b128 v[34:37], v100 offset:47808
	ds_read_b128 v[38:41], v100 offset:47824
	v_add_f32_e32 v140, v110, v111
	v_add_f32_e32 v141, v112, v113
	v_pk_mul_f32 v[114:115], v[84:85], v[50:51]
	v_add_f32_dpp v140, v140, v140 quad_perm:[1,0,3,2] row_mask:0xf bank_mask:0xf bound_ctrl:1
	v_add_f32_dpp v141, v141, v141 quad_perm:[1,0,3,2] row_mask:0xf bank_mask:0xf bound_ctrl:1
	v_pk_mul_f32 v[116:117], v[86:87], v[52:53]
	v_add_f32_dpp v140, v140, v140 quad_perm:[2,3,0,1] row_mask:0xf bank_mask:0xf bound_ctrl:1
	v_add_f32_dpp v141, v141, v141 quad_perm:[2,3,0,1] row_mask:0xf bank_mask:0xf bound_ctrl:1
	v_pk_mul_f32 v[118:119], v[88:89], v[46:47]
	v_add_f32_dpp v140, v140, v140 row_half_mirror row_mask:0xf bank_mask:0xf bound_ctrl:1
	v_add_f32_dpp v141, v141, v141 row_half_mirror row_mask:0xf bank_mask:0xf bound_ctrl:1
	v_pk_mul_f32 v[120:121], v[90:91], v[48:49]
	ds_read_b128 v[26:29], v100 offset:48064
	ds_read_b128 v[30:33], v100 offset:48080
	v_mul_f32_e32 v142, v140, v98
	v_mul_f32_e32 v143, v99, v0
	ds_read_b32 v94, v101 offset:48320
	v_add_f32_e32 v141, v142, v141
	ds_read_b64 v[96:97], v1 offset:48576
	v_add_f32_e32 v141, v143, v141
	v_pk_fma_f32 v[114:115], v[140:141], v[62:63], v[114:115] op_sel_hi:[0,1,1]
	v_pk_fma_f32 v[116:117], v[140:141], v[64:65], v[116:117] op_sel_hi:[0,1,1]
	v_cvt_pk_bf16_f32 v142, v141, v141
	v_pk_fma_f32 v[84:85], v[0:1], v[54:55], v[114:115] op_sel_hi:[0,1,1]
	global_store_short v157, v142, s[100:101]
	v_pk_fma_f32 v[118:119], v[140:141], v[58:59], v[118:119] op_sel_hi:[0,1,1]
	v_pk_fma_f32 v[86:87], v[0:1], v[56:57], v[116:117] op_sel_hi:[0,1,1]
	v_pk_fma_f32 v[120:121], v[140:141], v[60:61], v[120:121] op_sel_hi:[0,1,1]
	v_pk_fma_f32 v[88:89], v[0:1], v[42:43], v[118:119] op_sel_hi:[0,1,1]
	v_pk_fma_f32 v[90:91], v[0:1], v[44:45], v[120:121] op_sel_hi:[0,1,1]
	s_waitcnt lgkmcnt(0)
	v_pk_fma_f32 v[106:107], v[84:85], v[34:35], 0 op_sel_hi:[1,1,0]
	v_pk_fma_f32 v[108:109], v[84:85], v[22:23], 0 op_sel_hi:[1,1,0]
	ds_read_b128 v[70:73], v100 offset:48608
	ds_read_b128 v[66:69], v100 offset:48624
	v_pk_fma_f32 v[106:107], v[86:87], v[36:37], v[106:107]
	v_pk_fma_f32 v[108:109], v[86:87], v[24:25], v[108:109]
	ds_read_b128 v[50:53], v100 offset:48864
	ds_read_b128 v[46:49], v100 offset:48880
	v_pk_fma_f32 v[106:107], v[88:89], v[38:39], v[106:107]
	v_pk_fma_f32 v[108:109], v[88:89], v[18:19], v[108:109]
	ds_read_b128 v[54:57], v100 offset:49120
	ds_read_b128 v[42:45], v100 offset:49136
	v_pk_fma_f32 v[106:107], v[90:91], v[40:41], v[106:107]
	v_pk_fma_f32 v[108:109], v[90:91], v[20:21], v[108:109]
	ds_read_b128 v[78:81], v100 offset:49376
	ds_read_b128 v[74:77], v100 offset:49392
	v_add_f32_e32 v130, v106, v107
	v_add_f32_e32 v131, v108, v109
	v_pk_mul_f32 v[114:115], v[84:85], v[2:3]
	v_add_f32_dpp v130, v130, v130 quad_perm:[1,0,3,2] row_mask:0xf bank_mask:0xf bound_ctrl:1
	v_add_f32_dpp v131, v131, v131 quad_perm:[1,0,3,2] row_mask:0xf bank_mask:0xf bound_ctrl:1
	v_pk_mul_f32 v[116:117], v[86:87], v[4:5]
	v_add_f32_dpp v130, v130, v130 quad_perm:[2,3,0,1] row_mask:0xf bank_mask:0xf bound_ctrl:1
	v_add_f32_dpp v131, v131, v131 quad_perm:[2,3,0,1] row_mask:0xf bank_mask:0xf bound_ctrl:1
	v_pk_mul_f32 v[118:119], v[88:89], v[6:7]
	v_add_f32_dpp v130, v130, v130 row_half_mirror row_mask:0xf bank_mask:0xf bound_ctrl:1
	v_add_f32_dpp v131, v131, v131 row_half_mirror row_mask:0xf bank_mask:0xf bound_ctrl:1
	v_pk_mul_f32 v[120:121], v[90:91], v[8:9]
	ds_read_b128 v[62:65], v100 offset:49632
	ds_read_b128 v[58:61], v100 offset:49648
	v_mul_f32_e32 v132, v130, v96
	v_mul_f32_e32 v133, v97, v94
	ds_read_b32 v0, v101 offset:49888
	v_add_f32_e32 v131, v132, v131
	ds_read_b64 v[98:99], v1 offset:50144
	v_add_f32_e32 v131, v133, v131
	v_pk_fma_f32 v[114:115], v[130:131], v[26:27], v[114:115] op_sel_hi:[0,1,1]
	v_pk_fma_f32 v[116:117], v[130:131], v[28:29], v[116:117] op_sel_hi:[0,1,1]
	v_cvt_pk_bf16_f32 v132, v131, v131
	v_pk_fma_f32 v[84:85], v[94:95], v[10:11], v[114:115] op_sel_hi:[0,1,1]
	global_store_short v158, v132, s[100:101]
	v_pk_fma_f32 v[118:119], v[130:131], v[30:31], v[118:119] op_sel_hi:[0,1,1]
	v_pk_fma_f32 v[86:87], v[94:95], v[12:13], v[116:117] op_sel_hi:[0,1,1]
	v_pk_fma_f32 v[120:121], v[130:131], v[32:33], v[120:121] op_sel_hi:[0,1,1]
	v_pk_fma_f32 v[88:89], v[94:95], v[14:15], v[118:119] op_sel_hi:[0,1,1]
	v_pk_fma_f32 v[90:91], v[94:95], v[16:17], v[120:121] op_sel_hi:[0,1,1]
	s_waitcnt lgkmcnt(0)
	v_pk_fma_f32 v[110:111], v[84:85], v[78:79], 0 op_sel_hi:[1,1,0]
	v_pk_fma_f32 v[112:113], v[84:85], v[70:71], 0 op_sel_hi:[1,1,0]
	ds_read_b128 v[22:25], v100 offset:50176
	ds_read_b128 v[18:21], v100 offset:50192
	v_pk_fma_f32 v[110:111], v[86:87], v[80:81], v[110:111]
	v_pk_fma_f32 v[112:113], v[86:87], v[72:73], v[112:113]
	ds_read_b128 v[2:5], v100 offset:50432
	ds_read_b128 v[6:9], v100 offset:50448
	v_pk_fma_f32 v[110:111], v[88:89], v[74:75], v[110:111]
	v_pk_fma_f32 v[112:113], v[88:89], v[66:67], v[112:113]
	ds_read_b128 v[10:13], v100 offset:50688
	ds_read_b128 v[14:17], v100 offset:50704
	v_pk_fma_f32 v[110:111], v[90:91], v[76:77], v[110:111]
	v_pk_fma_f32 v[112:113], v[90:91], v[68:69], v[112:113]
	ds_read_b128 v[34:37], v100 offset:50944
	ds_read_b128 v[38:41], v100 offset:50960
	v_add_f32_e32 v140, v110, v111
	v_add_f32_e32 v141, v112, v113
	v_pk_mul_f32 v[114:115], v[84:85], v[50:51]
	v_add_f32_dpp v140, v140, v140 quad_perm:[1,0,3,2] row_mask:0xf bank_mask:0xf bound_ctrl:1
	v_add_f32_dpp v141, v141, v141 quad_perm:[1,0,3,2] row_mask:0xf bank_mask:0xf bound_ctrl:1
	v_pk_mul_f32 v[116:117], v[86:87], v[52:53]
	v_add_f32_dpp v140, v140, v140 quad_perm:[2,3,0,1] row_mask:0xf bank_mask:0xf bound_ctrl:1
	v_add_f32_dpp v141, v141, v141 quad_perm:[2,3,0,1] row_mask:0xf bank_mask:0xf bound_ctrl:1
	v_pk_mul_f32 v[118:119], v[88:89], v[46:47]
	v_add_f32_dpp v140, v140, v140 row_half_mirror row_mask:0xf bank_mask:0xf bound_ctrl:1
	v_add_f32_dpp v141, v141, v141 row_half_mirror row_mask:0xf bank_mask:0xf bound_ctrl:1
	v_pk_mul_f32 v[120:121], v[90:91], v[48:49]
	ds_read_b128 v[26:29], v100 offset:51200
	ds_read_b128 v[30:33], v100 offset:51216
	v_mul_f32_e32 v142, v140, v98
	v_mul_f32_e32 v143, v99, v0
	ds_read_b32 v94, v101 offset:51456
	v_add_f32_e32 v141, v142, v141
	ds_read_b64 v[96:97], v1 offset:51712
	v_add_f32_e32 v141, v143, v141
	v_pk_fma_f32 v[114:115], v[140:141], v[62:63], v[114:115] op_sel_hi:[0,1,1]
	v_pk_fma_f32 v[116:117], v[140:141], v[64:65], v[116:117] op_sel_hi:[0,1,1]
	v_cvt_pk_bf16_f32 v142, v141, v141
	v_pk_fma_f32 v[84:85], v[0:1], v[54:55], v[114:115] op_sel_hi:[0,1,1]
	global_store_short v159, v142, s[100:101]
	v_pk_fma_f32 v[118:119], v[140:141], v[58:59], v[118:119] op_sel_hi:[0,1,1]
	v_pk_fma_f32 v[86:87], v[0:1], v[56:57], v[116:117] op_sel_hi:[0,1,1]
	v_pk_fma_f32 v[120:121], v[140:141], v[60:61], v[120:121] op_sel_hi:[0,1,1]
	v_pk_fma_f32 v[88:89], v[0:1], v[42:43], v[118:119] op_sel_hi:[0,1,1]
	v_pk_fma_f32 v[90:91], v[0:1], v[44:45], v[120:121] op_sel_hi:[0,1,1]
	s_branch .LBB0_852
